# loading wave raises its priority for the load segment and drops it before the pre-MMA barrier (MFMA segments stay instruction-pure), on top of the K-loop setprio/lgkmcnt removal
# speedup vs baseline: 1.0024x; 1.0024x over previous
; #define PG8_STAGE(bufoff, gbase, voff) do { _Pragma("unroll") for (int _i = 0; _i < 2; ++_i) \
;         __builtin_amdgcn_global_load_lds((const unsigned*)((const char*)(gbase) + (voff)[_i]), (LAS unsigned*)(lds + (bufoff) + ldsw + _i * 8192), 16, 0, 0); } while (0)
; #define PG8_LDA(dst, b, h) do { _Pragma("unroll") for (int m = 0; m < 4; ++m) _Pragma("unroll") for (int k = 0; k < 2; ++k) dst[m][k] = *(const LAS bf16x8*)(lds + PG8_SA(b, h) + aoff + m * 2048 + k * 1024); } while (0)
; #define PG8_LDB(dst, b, h) do { _Pragma("unroll") for (int n = 0; n < 2; ++n) _Pragma("unroll") for (int k = 0; k < 2; ++k) dst[n][k] = *(const LAS bf16x8*)(lds + PG8_SB(b, h) + boff + n * 2048 + k * 1024); } while (0)
; #define PG8_MMA(ai, bj, At, Bt) do { __builtin_amdgcn_s_setprio(1); _Pragma("unroll") for (int m = 0; m < 4; ++m) _Pragma("unroll") for (int n = 0; n < 2; ++n) _Pragma("unroll") for (int k = 0; k < 2; ++k) \
;         acc[ai][bj][m][n] = __builtin_amdgcn_mfma_f32_16x16x32_bf16(Bt[n][k], At[m][k], acc[ai][bj][m][n], 0, 0, 0); __builtin_amdgcn_s_setprio(0); } while (0)
; #define PG8_WAIT_V(n) asm volatile("s_waitcnt vmcnt(" #n ")" ::: "memory")
; #define PG8_WAIT_L(n) asm volatile("s_waitcnt lgkmcnt(" #n ")" ::: "memory")
; #define PG8_BAR __builtin_amdgcn_s_barrier()
; #define PG8_SCHED __builtin_amdgcn_sched_barrier(0)
; template <class Epi, class Sched>
; DI void gemm_phase(LAS unsigned char* lds, const int K, const Sched& S, const Epi& E, const int wid) {
;     ...
;             const bool last = (t == nt - 2);
;             const char* a1 = cA + (size_t)(t + 1) * kstep;
;             const char* a2 = last ? nA : cA + (size_t)(t + 2) * kstep; const char* b2 = last ? nB : cB + (size_t)(t + 2) * kstep;
;             const char* a3 = a2 + kstep; const char* b3 = b2 + kstep;
;             if (last && has_next) S.a_ready(nxt);
;             PG8_LDB(B0, 0, 0); PG8_LDB(B1, 0, 1); PG8_SCHED; PG8_LDA(At, 0, 0); PG8_STAGE(PG8_SA(1, 1), a1 + hstep, voffA);
;             PG8_WAIT_V(8); PG8_WAIT_L(0); PG8_BAR; PG8_MMA(0, 0, At, B0); PG8_MMA(0, 1, At, B1); PG8_BAR; PG8_SCHED;
;             PG8_LDA(At, 0, 1); PG8_STAGE(PG8_SB(0, 0), b2, voffB); PG8_STAGE(PG8_SB(0, 1), b2 + hstep, voffB); PG8_STAGE(PG8_SA(0, 0), a2, voffA);
;             PG8_WAIT_V(8); PG8_WAIT_L(0); PG8_BAR; PG8_MMA(1, 0, At, B0); PG8_MMA(1, 1, At, B1); PG8_BAR; PG8_SCHED;
.LBB0_96:
	ds_read_b128 v[128:131], v179
	ds_read_b128 v[132:135], v179 offset:1024
	ds_read_b128 v[136:139], v179 offset:2048
	ds_read_b128 v[140:143], v179 offset:3072
	ds_read_b128 v[144:147], v180
	ds_read_b128 v[164:167], v180 offset:1024
	ds_read_b128 v[168:171], v180 offset:2048
	ds_read_b128 v[172:175], v180 offset:3072
	s_add_u32 s18, s4, 0xfff80080
	s_addc_u32 s19, s5, -1
	s_cmp_eq_u32 s17, 28
	s_cselect_b32 s69, s9, s19
	s_cselect_b32 s68, s10, s18
	s_cselect_b32 s57, s11, s16
	s_cselect_b32 s56, s14, s15
	v_lshl_add_u64 v[204:205], s[4:5], 0, v[156:157]
	s_add_i32 m0, s22, 0xc000
	ds_read_b128 v[184:187], v181
	ds_read_b128 v[188:191], v181 offset:1024
	ds_read_b128 v[192:195], v181 offset:2048
	ds_read_b128 v[196:199], v181 offset:3072
	ds_read_b128 v[200:203], v181 offset:4096
	ds_read_b128 v[208:211], v181 offset:5120
	ds_read_b128 v[212:215], v181 offset:6144
	ds_read_b128 v[216:219], v181 offset:7168
	global_load_lds_dwordx4 v[204:205], off
	v_lshl_add_u64 v[204:205], s[4:5], 0, v[158:159]
	s_add_i32 m0, s22, 0xe000
	s_nop 0
	global_load_lds_dwordx4 v[204:205], off
	s_waitcnt vmcnt(8)
	s_waitcnt lgkmcnt(0)
	s_setprio 0
	s_barrier
	v_mfma_f32_16x16x32_bf16 v[124:127], v[128:131], v[184:187], v[124:127]
	v_mfma_f32_16x16x32_bf16 v[120:123], v[136:139], v[184:187], v[120:123]
	v_mfma_f32_16x16x32_bf16 v[116:119], v[128:131], v[192:195], v[116:119]
	v_mfma_f32_16x16x32_bf16 v[112:115], v[136:139], v[192:195], v[112:115]
	v_mfma_f32_16x16x32_bf16 v[100:103], v[128:131], v[200:203], v[100:103]
	v_mfma_f32_16x16x32_bf16 v[96:99], v[136:139], v[200:203], v[96:99]
	v_mfma_f32_16x16x32_bf16 v[84:87], v[128:131], v[212:215], v[84:87]
	v_mfma_f32_16x16x32_bf16 v[80:83], v[136:139], v[212:215], v[80:83]
	v_mfma_f32_16x16x32_bf16 v[124:127], v[132:135], v[188:191], v[124:127]
	v_mfma_f32_16x16x32_bf16 v[120:123], v[140:143], v[188:191], v[120:123]
	v_mfma_f32_16x16x32_bf16 v[116:119], v[132:135], v[196:199], v[116:119]
	v_mfma_f32_16x16x32_bf16 v[112:115], v[140:143], v[196:199], v[112:115]
	v_mfma_f32_16x16x32_bf16 v[100:103], v[132:135], v[208:211], v[100:103]
	v_mfma_f32_16x16x32_bf16 v[96:99], v[140:143], v[208:211], v[96:99]
	v_mfma_f32_16x16x32_bf16 v[84:87], v[132:135], v[216:219], v[84:87]
	v_mfma_f32_16x16x32_bf16 v[80:83], v[140:143], v[216:219], v[80:83]
	v_mfma_f32_16x16x32_bf16 v[108:111], v[144:147], v[184:187], v[108:111]
	v_mfma_f32_16x16x32_bf16 v[104:107], v[168:171], v[184:187], v[104:107]
	v_mfma_f32_16x16x32_bf16 v[92:95], v[144:147], v[192:195], v[92:95]
	v_mfma_f32_16x16x32_bf16 v[88:91], v[168:171], v[192:195], v[88:91]
	v_mfma_f32_16x16x32_bf16 v[76:79], v[144:147], v[200:203], v[76:79]
	v_mfma_f32_16x16x32_bf16 v[72:75], v[168:171], v[200:203], v[72:75]
	v_mfma_f32_16x16x32_bf16 v[68:71], v[144:147], v[212:215], v[68:71]
	v_mfma_f32_16x16x32_bf16 v[64:67], v[168:171], v[212:215], v[64:67]
	v_mfma_f32_16x16x32_bf16 v[108:111], v[164:167], v[188:191], v[108:111]
	v_mfma_f32_16x16x32_bf16 v[104:107], v[172:175], v[188:191], v[104:107]
	v_mfma_f32_16x16x32_bf16 v[92:95], v[164:167], v[196:199], v[92:95]
	v_mfma_f32_16x16x32_bf16 v[88:91], v[172:175], v[196:199], v[88:91]
	v_mfma_f32_16x16x32_bf16 v[76:79], v[164:167], v[208:211], v[76:79]
	v_mfma_f32_16x16x32_bf16 v[72:75], v[172:175], v[208:211], v[72:75]
	v_mfma_f32_16x16x32_bf16 v[68:71], v[164:167], v[216:219], v[68:71]
	v_mfma_f32_16x16x32_bf16 v[64:67], v[172:175], v[216:219], v[64:67]
	s_barrier
	s_setprio 1
	s_add_i32 s18, s13, s95
	v_lshl_add_u64 v[204:205], s[56:57], 0, v[150:151]
	s_mov_b32 m0, s18
	ds_read_b128 v[184:187], v181 offset:16384
	ds_read_b128 v[188:191], v181 offset:17408
	ds_read_b128 v[192:195], v181 offset:18432
	ds_read_b128 v[196:199], v181 offset:19456
	ds_read_b128 v[200:203], v181 offset:20480
	ds_read_b128 v[208:211], v181 offset:21504
	ds_read_b128 v[212:215], v181 offset:22528
	ds_read_b128 v[216:219], v181 offset:23552
	global_load_lds_dwordx4 v[204:205], off
	s_add_i32 m0, s18, 0x2000
	s_add_u32 s18, s56, 0x80000
	v_lshl_add_u64 v[220:221], s[56:57], 0, v[154:155]
	s_addc_u32 s19, s57, 0
	s_add_i32 s20, s24, s95
	global_load_lds_dwordx4 v[220:221], off
	v_lshl_add_u64 v[222:223], s[18:19], 0, v[150:151]
	s_mov_b32 m0, s20
	v_lshl_add_u64 v[224:225], s[68:69], 0, v[152:153]
	global_load_lds_dwordx4 v[222:223], off
	v_lshl_add_u64 v[222:223], s[18:19], 0, v[154:155]
	s_add_i32 m0, s20, 0x2000
	s_nop 0
	global_load_lds_dwordx4 v[222:223], off
	v_lshl_add_u64 v[222:223], s[68:69], 0, v[148:149]
	s_mov_b32 m0, s22
	s_nop 0
	global_load_lds_dwordx4 v[222:223], off
	s_mov_b32 m0, s23
	s_nop 0
	global_load_lds_dwordx4 v[224:225], off
	s_waitcnt vmcnt(8)
	s_waitcnt lgkmcnt(0)
	s_setprio 0
	s_barrier
; #define PG8_STAGE(bufoff, gbase, voff) do { _Pragma("unroll") for (int _i = 0; _i < 2; ++_i) \
;         __builtin_amdgcn_global_load_lds((const unsigned*)((const char*)(gbase) + (voff)[_i]), (LAS unsigned*)(lds + (bufoff) + ldsw + _i * 8192), 16, 0, 0); } while (0)
; #define PG8_LDA(dst, b, h) do { _Pragma("unroll") for (int m = 0; m < 4; ++m) _Pragma("unroll") for (int k = 0; k < 2; ++k) dst[m][k] = *(const LAS bf16x8*)(lds + PG8_SA(b, h) + aoff + m * 2048 + k * 1024); } while (0)
; #define PG8_LDB(dst, b, h) do { _Pragma("unroll") for (int n = 0; n < 2; ++n) _Pragma("unroll") for (int k = 0; k < 2; ++k) dst[n][k] = *(const LAS bf16x8*)(lds + PG8_SB(b, h) + boff + n * 2048 + k * 1024); } while (0)
; #define PG8_MMA(ai, bj, At, Bt) do { __builtin_amdgcn_s_setprio(1); _Pragma("unroll") for (int m = 0; m < 4; ++m) _Pragma("unroll") for (int n = 0; n < 2; ++n) _Pragma("unroll") for (int k = 0; k < 2; ++k) \
;         acc[ai][bj][m][n] = __builtin_amdgcn_mfma_f32_16x16x32_bf16(Bt[n][k], At[m][k], acc[ai][bj][m][n], 0, 0, 0); __builtin_amdgcn_s_setprio(0); } while (0)
; #define PG8_WAIT_V(n) asm volatile("s_waitcnt vmcnt(" #n ")" ::: "memory")
; #define PG8_WAIT_L(n) asm volatile("s_waitcnt lgkmcnt(" #n ")" ::: "memory")
; #define PG8_BAR __builtin_amdgcn_s_barrier()
; #define PG8_SCHED __builtin_amdgcn_sched_barrier(0)
; template <class Epi, class Sched>
; DI void gemm_phase(LAS unsigned char* lds, const int K, const Sched& S, const Epi& E, const int wid) {
;     ...
;             PG8_WAIT_V(8); PG8_WAIT_L(0); PG8_BAR; PG8_MMA(1, 0, At, B0); PG8_MMA(1, 1, At, B1); PG8_BAR; PG8_SCHED;
;             PG8_LDB(B0, 1, 0); PG8_LDB(B1, 1, 1); PG8_SCHED; PG8_LDA(At, 1, 0); PG8_STAGE(PG8_SA(0, 1), a2 + hstep, voffA);
;             PG8_WAIT_V(8); PG8_WAIT_L(0); PG8_BAR; PG8_MMA(0, 0, At, B0); PG8_MMA(0, 1, At, B1); PG8_BAR; PG8_SCHED;
	v_mfma_f32_16x16x32_bf16 v[60:63], v[128:131], v[184:187], v[60:63]
	v_mfma_f32_16x16x32_bf16 v[56:59], v[136:139], v[184:187], v[56:59]
	v_mfma_f32_16x16x32_bf16 v[52:55], v[128:131], v[192:195], v[52:55]
	v_mfma_f32_16x16x32_bf16 v[48:51], v[136:139], v[192:195], v[48:51]
	v_mfma_f32_16x16x32_bf16 v[36:39], v[128:131], v[200:203], v[36:39]
	v_mfma_f32_16x16x32_bf16 v[32:35], v[136:139], v[200:203], v[32:35]
	v_mfma_f32_16x16x32_bf16 v[20:23], v[128:131], v[212:215], v[20:23]
	v_mfma_f32_16x16x32_bf16 v[16:19], v[136:139], v[212:215], v[16:19]
	v_mfma_f32_16x16x32_bf16 v[60:63], v[132:135], v[188:191], v[60:63]
	v_mfma_f32_16x16x32_bf16 v[56:59], v[140:143], v[188:191], v[56:59]
	v_mfma_f32_16x16x32_bf16 v[52:55], v[132:135], v[196:199], v[52:55]
	v_mfma_f32_16x16x32_bf16 v[48:51], v[140:143], v[196:199], v[48:51]
	v_mfma_f32_16x16x32_bf16 v[36:39], v[132:135], v[208:211], v[36:39]
	v_mfma_f32_16x16x32_bf16 v[32:35], v[140:143], v[208:211], v[32:35]
	v_mfma_f32_16x16x32_bf16 v[20:23], v[132:135], v[216:219], v[20:23]
	v_mfma_f32_16x16x32_bf16 v[16:19], v[140:143], v[216:219], v[16:19]
	v_mfma_f32_16x16x32_bf16 v[44:47], v[144:147], v[184:187], v[44:47]
	v_mfma_f32_16x16x32_bf16 v[40:43], v[168:171], v[184:187], v[40:43]
	v_mfma_f32_16x16x32_bf16 v[28:31], v[144:147], v[192:195], v[28:31]
	v_mfma_f32_16x16x32_bf16 v[24:27], v[168:171], v[192:195], v[24:27]
	v_mfma_f32_16x16x32_bf16 v[12:15], v[144:147], v[200:203], v[12:15]
	v_mfma_f32_16x16x32_bf16 v[8:11], v[168:171], v[200:203], v[8:11]
	v_mfma_f32_16x16x32_bf16 v[4:7], v[144:147], v[212:215], v[4:7]
	v_mfma_f32_16x16x32_bf16 v[0:3], v[168:171], v[212:215], v[0:3]
	v_mfma_f32_16x16x32_bf16 v[44:47], v[164:167], v[188:191], v[44:47]
	v_mfma_f32_16x16x32_bf16 v[40:43], v[172:175], v[188:191], v[40:43]
	v_mfma_f32_16x16x32_bf16 v[28:31], v[164:167], v[196:199], v[28:31]
	v_mfma_f32_16x16x32_bf16 v[24:27], v[172:175], v[196:199], v[24:27]
	v_mfma_f32_16x16x32_bf16 v[12:15], v[164:167], v[208:211], v[12:15]
	v_mfma_f32_16x16x32_bf16 v[8:11], v[172:175], v[208:211], v[8:11]
	v_mfma_f32_16x16x32_bf16 v[4:7], v[164:167], v[216:219], v[4:7]
	v_mfma_f32_16x16x32_bf16 v[0:3], v[172:175], v[216:219], v[0:3]
	s_barrier
	s_setprio 1
	s_add_i32 s20, 0, 0x18000
	s_add_i32 s21, 0, 0x1c000
	v_add_u32_e32 v140, s20, v178
	v_add_u32_e32 v172, s21, v178
	ds_read_b128 v[128:131], v140
	ds_read_b128 v[132:135], v140 offset:1024
	ds_read_b128 v[136:139], v140 offset:2048
	ds_read_b128 v[140:143], v140 offset:3072
	ds_read_b128 v[144:147], v172
	ds_read_b128 v[164:167], v172 offset:1024
	ds_read_b128 v[168:171], v172 offset:2048
	ds_read_b128 v[172:175], v172 offset:3072
	s_add_u32 s18, s68, 0x80000
	s_addc_u32 s19, s69, 0
	s_mov_b32 m0, s26
	v_lshl_add_u64 v[226:227], s[18:19], 0, v[148:149]
	ds_read_b128 v[184:187], v181 offset:32768
	ds_read_b128 v[188:191], v181 offset:33792
	ds_read_b128 v[192:195], v181 offset:34816
	ds_read_b128 v[196:199], v181 offset:35840
	ds_read_b128 v[200:203], v181 offset:36864
	ds_read_b128 v[208:211], v181 offset:37888
	ds_read_b128 v[212:215], v181 offset:38912
	ds_read_b128 v[216:219], v181 offset:39936
	global_load_lds_dwordx4 v[226:227], off
	v_lshl_add_u64 v[226:227], s[18:19], 0, v[152:153]
	s_mov_b32 m0, s27
	s_nop 0
	global_load_lds_dwordx4 v[226:227], off
	s_waitcnt vmcnt(8)
	s_waitcnt lgkmcnt(0)
	s_setprio 0
	s_barrier
	v_mfma_f32_16x16x32_bf16 v[124:127], v[128:131], v[184:187], v[124:127]
	v_mfma_f32_16x16x32_bf16 v[120:123], v[136:139], v[184:187], v[120:123]
	v_mfma_f32_16x16x32_bf16 v[116:119], v[128:131], v[192:195], v[116:119]
	v_mfma_f32_16x16x32_bf16 v[112:115], v[136:139], v[192:195], v[112:115]
	v_mfma_f32_16x16x32_bf16 v[100:103], v[128:131], v[200:203], v[100:103]
	v_mfma_f32_16x16x32_bf16 v[96:99], v[136:139], v[200:203], v[96:99]
	v_mfma_f32_16x16x32_bf16 v[84:87], v[128:131], v[212:215], v[84:87]
	v_mfma_f32_16x16x32_bf16 v[80:83], v[136:139], v[212:215], v[80:83]
	v_mfma_f32_16x16x32_bf16 v[124:127], v[132:135], v[188:191], v[124:127]
	v_mfma_f32_16x16x32_bf16 v[120:123], v[140:143], v[188:191], v[120:123]
	v_mfma_f32_16x16x32_bf16 v[116:119], v[132:135], v[196:199], v[116:119]
	v_mfma_f32_16x16x32_bf16 v[112:115], v[140:143], v[196:199], v[112:115]
	v_mfma_f32_16x16x32_bf16 v[100:103], v[132:135], v[208:211], v[100:103]
	v_mfma_f32_16x16x32_bf16 v[96:99], v[140:143], v[208:211], v[96:99]
	v_mfma_f32_16x16x32_bf16 v[84:87], v[132:135], v[216:219], v[84:87]
	v_mfma_f32_16x16x32_bf16 v[80:83], v[140:143], v[216:219], v[80:83]
	v_mfma_f32_16x16x32_bf16 v[108:111], v[144:147], v[184:187], v[108:111]
	v_mfma_f32_16x16x32_bf16 v[104:107], v[168:171], v[184:187], v[104:107]
	v_mfma_f32_16x16x32_bf16 v[92:95], v[144:147], v[192:195], v[92:95]
	v_mfma_f32_16x16x32_bf16 v[88:91], v[168:171], v[192:195], v[88:91]
	v_mfma_f32_16x16x32_bf16 v[76:79], v[144:147], v[200:203], v[76:79]
	v_mfma_f32_16x16x32_bf16 v[72:75], v[168:171], v[200:203], v[72:75]
	v_mfma_f32_16x16x32_bf16 v[68:71], v[144:147], v[212:215], v[68:71]
	v_mfma_f32_16x16x32_bf16 v[64:67], v[168:171], v[212:215], v[64:67]
	v_mfma_f32_16x16x32_bf16 v[108:111], v[164:167], v[188:191], v[108:111]
	v_mfma_f32_16x16x32_bf16 v[104:107], v[172:175], v[188:191], v[104:107]
	v_mfma_f32_16x16x32_bf16 v[92:95], v[164:167], v[196:199], v[92:95]
	v_mfma_f32_16x16x32_bf16 v[88:91], v[172:175], v[196:199], v[88:91]
	v_mfma_f32_16x16x32_bf16 v[76:79], v[164:167], v[208:211], v[76:79]
	v_mfma_f32_16x16x32_bf16 v[72:75], v[172:175], v[208:211], v[72:75]
	v_mfma_f32_16x16x32_bf16 v[68:71], v[164:167], v[216:219], v[68:71]
	v_mfma_f32_16x16x32_bf16 v[64:67], v[172:175], v[216:219], v[64:67]
	s_barrier
; #define PG8_STAGE(bufoff, gbase, voff) do { _Pragma("unroll") for (int _i = 0; _i < 2; ++_i) \
;         __builtin_amdgcn_global_load_lds((const unsigned*)((const char*)(gbase) + (voff)[_i]), (LAS unsigned*)(lds + (bufoff) + ldsw + _i * 8192), 16, 0, 0); } while (0)
; #define PG8_LDA(dst, b, h) do { _Pragma("unroll") for (int m = 0; m < 4; ++m) _Pragma("unroll") for (int k = 0; k < 2; ++k) dst[m][k] = *(const LAS bf16x8*)(lds + PG8_SA(b, h) + aoff + m * 2048 + k * 1024); } while (0)
; #define PG8_MMA(ai, bj, At, Bt) do { __builtin_amdgcn_s_setprio(1); _Pragma("unroll") for (int m = 0; m < 4; ++m) _Pragma("unroll") for (int n = 0; n < 2; ++n) _Pragma("unroll") for (int k = 0; k < 2; ++k) \
;         acc[ai][bj][m][n] = __builtin_amdgcn_mfma_f32_16x16x32_bf16(Bt[n][k], At[m][k], acc[ai][bj][m][n], 0, 0, 0); __builtin_amdgcn_s_setprio(0); } while (0)
; #define PG8_WAIT_V(n) asm volatile("s_waitcnt vmcnt(" #n ")" ::: "memory")
; #define PG8_WAIT_L(n) asm volatile("s_waitcnt lgkmcnt(" #n ")" ::: "memory")
; #define PG8_BAR __builtin_amdgcn_s_barrier()
; #define PG8_SCHED __builtin_amdgcn_sched_barrier(0)
; template <class Epi, class Sched>
; DI void gemm_phase(LAS unsigned char* lds, const int K, const Sched& S, const Epi& E, const int wid) {
;     ...
;             PG8_LDA(At, 1, 1); PG8_STAGE(PG8_SB(1, 0), b3, voffB); PG8_STAGE(PG8_SB(1, 1), b3 + hstep, voffB); PG8_STAGE(PG8_SA(1, 0), a3, voffA);
;             PG8_WAIT_V(8); PG8_WAIT_L(0); PG8_BAR; PG8_MMA(1, 0, At, B0); PG8_MMA(1, 1, At, B1); PG8_BAR; PG8_SCHED;
;         }
	s_setprio 1
	s_add_i32 s18, s20, s95
	v_lshl_add_u64 v[204:205], v[204:205], 0, s[42:43]
	s_mov_b32 m0, s18
	ds_read_b128 v[184:187], v181 offset:49152
	ds_read_b128 v[188:191], v181 offset:50176
	ds_read_b128 v[192:195], v181 offset:51200
	ds_read_b128 v[196:199], v181 offset:52224
	ds_read_b128 v[200:203], v181 offset:53248
	ds_read_b128 v[208:211], v181 offset:54272
	ds_read_b128 v[212:215], v181 offset:55296
	ds_read_b128 v[216:219], v181 offset:56320
	global_load_lds_dwordx4 v[204:205], off
	s_add_i32 m0, s18, 0x2000
	s_add_u32 s18, s56, 0x80080
	v_lshl_add_u64 v[204:205], v[220:221], 0, s[42:43]
	s_addc_u32 s19, s57, 0
	s_add_i32 s20, s21, s95
	global_load_lds_dwordx4 v[204:205], off
	v_lshl_add_u64 v[204:205], s[18:19], 0, v[150:151]
	s_mov_b32 m0, s20
	s_nop 0
	global_load_lds_dwordx4 v[204:205], off
	v_lshl_add_u64 v[204:205], s[18:19], 0, v[154:155]
	s_add_i32 m0, s20, 0x2000
	s_nop 0
	global_load_lds_dwordx4 v[204:205], off
	v_lshl_add_u64 v[204:205], v[222:223], 0, s[42:43]
	s_mov_b32 m0, s94
	s_nop 0
	global_load_lds_dwordx4 v[204:205], off
	v_lshl_add_u64 v[204:205], v[224:225], 0, s[42:43]
	s_mov_b32 m0, s96
	s_nop 0
	global_load_lds_dwordx4 v[204:205], off
	s_waitcnt vmcnt(8)
	s_waitcnt lgkmcnt(0)
	s_setprio 0
	s_barrier
	v_mfma_f32_16x16x32_bf16 v[60:63], v[128:131], v[184:187], v[60:63]
	v_mfma_f32_16x16x32_bf16 v[56:59], v[136:139], v[184:187], v[56:59]
	v_mfma_f32_16x16x32_bf16 v[52:55], v[128:131], v[192:195], v[52:55]
	v_mfma_f32_16x16x32_bf16 v[48:51], v[136:139], v[192:195], v[48:51]
	v_mfma_f32_16x16x32_bf16 v[36:39], v[128:131], v[200:203], v[36:39]
	v_mfma_f32_16x16x32_bf16 v[32:35], v[136:139], v[200:203], v[32:35]
	v_mfma_f32_16x16x32_bf16 v[20:23], v[128:131], v[212:215], v[20:23]
	v_mfma_f32_16x16x32_bf16 v[16:19], v[136:139], v[212:215], v[16:19]
	v_mfma_f32_16x16x32_bf16 v[60:63], v[132:135], v[188:191], v[60:63]
	v_mfma_f32_16x16x32_bf16 v[56:59], v[140:143], v[188:191], v[56:59]
	v_mfma_f32_16x16x32_bf16 v[52:55], v[132:135], v[196:199], v[52:55]
	v_mfma_f32_16x16x32_bf16 v[48:51], v[140:143], v[196:199], v[48:51]
	v_mfma_f32_16x16x32_bf16 v[36:39], v[132:135], v[208:211], v[36:39]
	v_mfma_f32_16x16x32_bf16 v[32:35], v[140:143], v[208:211], v[32:35]
	v_mfma_f32_16x16x32_bf16 v[20:23], v[132:135], v[216:219], v[20:23]
	v_mfma_f32_16x16x32_bf16 v[16:19], v[140:143], v[216:219], v[16:19]
	v_mfma_f32_16x16x32_bf16 v[44:47], v[144:147], v[184:187], v[44:47]
	v_mfma_f32_16x16x32_bf16 v[40:43], v[168:171], v[184:187], v[40:43]
	v_mfma_f32_16x16x32_bf16 v[28:31], v[144:147], v[192:195], v[28:31]
	v_mfma_f32_16x16x32_bf16 v[24:27], v[168:171], v[192:195], v[24:27]
	v_mfma_f32_16x16x32_bf16 v[12:15], v[144:147], v[200:203], v[12:15]
	v_mfma_f32_16x16x32_bf16 v[8:11], v[168:171], v[200:203], v[8:11]
	v_mfma_f32_16x16x32_bf16 v[4:7], v[144:147], v[212:215], v[4:7]
	v_mfma_f32_16x16x32_bf16 v[0:3], v[168:171], v[212:215], v[0:3]
	v_mfma_f32_16x16x32_bf16 v[44:47], v[164:167], v[188:191], v[44:47]
	v_mfma_f32_16x16x32_bf16 v[40:43], v[172:175], v[188:191], v[40:43]
	v_mfma_f32_16x16x32_bf16 v[28:31], v[164:167], v[196:199], v[28:31]
	v_mfma_f32_16x16x32_bf16 v[24:27], v[172:175], v[196:199], v[24:27]
	v_mfma_f32_16x16x32_bf16 v[12:15], v[164:167], v[208:211], v[12:15]
	v_mfma_f32_16x16x32_bf16 v[8:11], v[172:175], v[208:211], v[8:11]
	v_mfma_f32_16x16x32_bf16 v[4:7], v[164:167], v[216:219], v[4:7]
	v_mfma_f32_16x16x32_bf16 v[0:3], v[172:175], v[216:219], v[0:3]
	s_barrier
	s_setprio 1
	s_add_i32 s17, s17, 2
	s_add_u32 s4, s4, 0x100
	s_addc_u32 s5, s5, 0
	s_add_u32 s15, s15, 0x100
	s_addc_u32 s16, s16, 0
	s_cmp_gt_u32 s17, 29
	s_cbranch_scc0 .LBB0_96
	v_readlane_b32 s4, v249, 25
	v_readlane_b32 s5, v249, 26
	s_and_b64 vcc, exec, s[4:5]
	s_cbranch_vccz .LBB0_99
	s_barrier

; #define PG8_STAGE(bufoff, gbase, voff) do { _Pragma("unroll") for (int _i = 0; _i < 2; ++_i) \
;         __builtin_amdgcn_global_load_lds((const unsigned*)((const char*)(gbase) + (voff)[_i]), (LAS unsigned*)(lds + (bufoff) + ldsw + _i * 8192), 16, 0, 0); } while (0)
; #define PG8_LDA(dst, b, h) do { _Pragma("unroll") for (int m = 0; m < 4; ++m) _Pragma("unroll") for (int k = 0; k < 2; ++k) dst[m][k] = *(const LAS bf16x8*)(lds + PG8_SA(b, h) + aoff + m * 2048 + k * 1024); } while (0)
; #define PG8_LDB(dst, b, h) do { _Pragma("unroll") for (int n = 0; n < 2; ++n) _Pragma("unroll") for (int k = 0; k < 2; ++k) dst[n][k] = *(const LAS bf16x8*)(lds + PG8_SB(b, h) + boff + n * 2048 + k * 1024); } while (0)
; #define PG8_MMA(ai, bj, At, Bt) do { __builtin_amdgcn_s_setprio(1); _Pragma("unroll") for (int m = 0; m < 4; ++m) _Pragma("unroll") for (int n = 0; n < 2; ++n) _Pragma("unroll") for (int k = 0; k < 2; ++k) \
;         acc[ai][bj][m][n] = __builtin_amdgcn_mfma_f32_16x16x32_bf16(Bt[n][k], At[m][k], acc[ai][bj][m][n], 0, 0, 0); __builtin_amdgcn_s_setprio(0); } while (0)
; #define PG8_WAIT_V(n) asm volatile("s_waitcnt vmcnt(" #n ")" ::: "memory")
; #define PG8_WAIT_L(n) asm volatile("s_waitcnt lgkmcnt(" #n ")" ::: "memory")
; #define PG8_BAR __builtin_amdgcn_s_barrier()
; #define PG8_SCHED __builtin_amdgcn_sched_barrier(0)
; template <class Epi, class Sched>
; DI void gemm_phase(LAS unsigned char* lds, const int K, const Sched& S, const Epi& E, const int wid) {
;     ...
;             const bool last = (t == nt - 2);
;             const char* a1 = cA + (size_t)(t + 1) * kstep;
;             const char* a2 = last ? nA : cA + (size_t)(t + 2) * kstep; const char* b2 = last ? nB : cB + (size_t)(t + 2) * kstep;
;             const char* a3 = a2 + kstep; const char* b3 = b2 + kstep;
;             if (last && has_next) S.a_ready(nxt);
;             PG8_LDB(B0, 0, 0); PG8_LDB(B1, 0, 1); PG8_SCHED; PG8_LDA(At, 0, 0); PG8_STAGE(PG8_SA(1, 1), a1 + hstep, voffA);
;             PG8_WAIT_V(8); PG8_WAIT_L(0); PG8_BAR; PG8_MMA(0, 0, At, B0); PG8_MMA(0, 1, At, B1); PG8_BAR; PG8_SCHED;
;             PG8_LDA(At, 0, 1); PG8_STAGE(PG8_SB(0, 0), b2, voffB); PG8_STAGE(PG8_SB(0, 1), b2 + hstep, voffB); PG8_STAGE(PG8_SA(0, 0), a2, voffA);
;             PG8_WAIT_V(8); PG8_WAIT_L(0); PG8_BAR; PG8_MMA(1, 0, At, B0); PG8_MMA(1, 1, At, B1); PG8_BAR; PG8_SCHED;
.LBB0_539:
	ds_read_b128 v[128:131], v208
	ds_read_b128 v[132:135], v208 offset:1024
	ds_read_b128 v[136:139], v208 offset:2048
	ds_read_b128 v[140:143], v208 offset:3072
	ds_read_b128 v[144:147], v209
	ds_read_b128 v[148:151], v209 offset:1024
	ds_read_b128 v[152:155], v209 offset:2048
	ds_read_b128 v[156:159], v209 offset:3072
	s_add_i32 s49, s4, 2
	s_add_u32 s0, s56, 0xfffc0080
	s_addc_u32 s1, s57, -1
	s_cmp_eq_u32 s30, s4
	s_cselect_b32 s4, s52, s45
	s_cselect_b32 s7, s51, s1
	s_cselect_b32 s6, s50, s0
	s_cselect_b32 s5, s53, s47
	s_add_i32 s89, s85, 0xc000
	v_lshl_add_u64 v[212:213], s[56:57], 0, v[184:185]
	s_mov_b32 m0, s89
	s_add_i32 s26, s85, 0xe000
	ds_read_b128 v[160:163], v210
	ds_read_b128 v[164:167], v210 offset:1024
	ds_read_b128 v[168:171], v210 offset:2048
	ds_read_b128 v[172:175], v210 offset:3072
	ds_read_b128 v[188:191], v210 offset:4096
	ds_read_b128 v[192:195], v210 offset:5120
	ds_read_b128 v[196:199], v210 offset:6144
	ds_read_b128 v[200:203], v210 offset:7168
	global_load_lds_dwordx4 v[212:213], off
	v_lshl_add_u64 v[212:213], s[56:57], 0, v[186:187]
	s_mov_b32 m0, s26
	s_nop 0
	global_load_lds_dwordx4 v[212:213], off
	s_waitcnt vmcnt(8)
	s_waitcnt lgkmcnt(0)
	s_setprio 0
	s_barrier
	v_mfma_f32_16x16x32_bf16 v[124:127], v[128:131], v[160:163], v[124:127]
	v_mfma_f32_16x16x32_bf16 v[120:123], v[136:139], v[160:163], v[120:123]
	v_mfma_f32_16x16x32_bf16 v[108:111], v[128:131], v[168:171], v[108:111]
	v_mfma_f32_16x16x32_bf16 v[104:107], v[136:139], v[168:171], v[104:107]
	v_mfma_f32_16x16x32_bf16 v[96:99], v[128:131], v[188:191], v[96:99]
	v_mfma_f32_16x16x32_bf16 v[88:91], v[136:139], v[188:191], v[88:91]
	v_mfma_f32_16x16x32_bf16 v[80:83], v[128:131], v[196:199], v[80:83]
	v_mfma_f32_16x16x32_bf16 v[72:75], v[136:139], v[196:199], v[72:75]
	v_mfma_f32_16x16x32_bf16 v[124:127], v[132:135], v[164:167], v[124:127]
	v_mfma_f32_16x16x32_bf16 v[120:123], v[140:143], v[164:167], v[120:123]
	v_mfma_f32_16x16x32_bf16 v[108:111], v[132:135], v[172:175], v[108:111]
	v_mfma_f32_16x16x32_bf16 v[104:107], v[140:143], v[172:175], v[104:107]
	v_mfma_f32_16x16x32_bf16 v[96:99], v[132:135], v[192:195], v[96:99]
	v_mfma_f32_16x16x32_bf16 v[88:91], v[140:143], v[192:195], v[88:91]
	v_mfma_f32_16x16x32_bf16 v[80:83], v[132:135], v[200:203], v[80:83]
	v_mfma_f32_16x16x32_bf16 v[72:75], v[140:143], v[200:203], v[72:75]
	v_mfma_f32_16x16x32_bf16 v[116:119], v[144:147], v[160:163], v[116:119]
	v_mfma_f32_16x16x32_bf16 v[112:115], v[152:155], v[160:163], v[112:115]
	v_mfma_f32_16x16x32_bf16 v[100:103], v[144:147], v[168:171], v[100:103]
	v_mfma_f32_16x16x32_bf16 v[92:95], v[152:155], v[168:171], v[92:95]
	v_mfma_f32_16x16x32_bf16 v[84:87], v[144:147], v[188:191], v[84:87]
	v_mfma_f32_16x16x32_bf16 v[76:79], v[152:155], v[188:191], v[76:79]
	v_mfma_f32_16x16x32_bf16 v[68:71], v[144:147], v[196:199], v[68:71]
	v_mfma_f32_16x16x32_bf16 v[64:67], v[152:155], v[196:199], v[64:67]
	v_mfma_f32_16x16x32_bf16 v[116:119], v[148:151], v[164:167], v[116:119]
	v_mfma_f32_16x16x32_bf16 v[112:115], v[156:159], v[164:167], v[112:115]
	v_mfma_f32_16x16x32_bf16 v[100:103], v[148:151], v[172:175], v[100:103]
	v_mfma_f32_16x16x32_bf16 v[92:95], v[156:159], v[172:175], v[92:95]
	v_mfma_f32_16x16x32_bf16 v[84:87], v[148:151], v[192:195], v[84:87]
	v_mfma_f32_16x16x32_bf16 v[76:79], v[156:159], v[192:195], v[76:79]
	v_mfma_f32_16x16x32_bf16 v[68:71], v[148:151], v[200:203], v[68:71]
	v_mfma_f32_16x16x32_bf16 v[64:67], v[156:159], v[200:203], v[64:67]
	s_barrier
	s_setprio 1
	s_add_i32 s27, s70, s95
	s_add_i32 s22, s27, 0x2000
	v_lshl_add_u64 v[212:213], s[4:5], 0, v[178:179]
	s_mov_b32 m0, s27
	s_add_u32 s0, s4, 0x40000
	ds_read_b128 v[160:163], v210 offset:16384
	ds_read_b128 v[164:167], v210 offset:17408
	ds_read_b128 v[168:171], v210 offset:18432
	ds_read_b128 v[172:175], v210 offset:19456
	ds_read_b128 v[188:191], v210 offset:20480
	ds_read_b128 v[192:195], v210 offset:21504
	ds_read_b128 v[196:199], v210 offset:22528
	ds_read_b128 v[200:203], v210 offset:23552
	global_load_lds_dwordx4 v[212:213], off
	v_lshl_add_u64 v[214:215], s[4:5], 0, v[182:183]
	s_mov_b32 m0, s22
	s_addc_u32 s1, s5, 0
	s_add_i32 s23, s2, s95
	global_load_lds_dwordx4 v[214:215], off
	v_lshl_add_u64 v[216:217], s[0:1], 0, v[178:179]
	s_mov_b32 m0, s23
	s_add_i32 s87, s23, 0x2000
	global_load_lds_dwordx4 v[216:217], off
	v_lshl_add_u64 v[216:217], s[0:1], 0, v[182:183]
	s_mov_b32 m0, s87
	v_lshl_add_u64 v[218:219], s[6:7], 0, v[180:181]
	global_load_lds_dwordx4 v[216:217], off
	v_lshl_add_u64 v[216:217], s[6:7], 0, v[176:177]
	s_mov_b32 m0, s85
	s_nop 0
	global_load_lds_dwordx4 v[216:217], off
	s_mov_b32 m0, s33
	s_nop 0
	global_load_lds_dwordx4 v[218:219], off
	s_waitcnt vmcnt(8)
	s_waitcnt lgkmcnt(0)
	s_setprio 0
	s_barrier
; #define PG8_STAGE(bufoff, gbase, voff) do { _Pragma("unroll") for (int _i = 0; _i < 2; ++_i) \
;         __builtin_amdgcn_global_load_lds((const unsigned*)((const char*)(gbase) + (voff)[_i]), (LAS unsigned*)(lds + (bufoff) + ldsw + _i * 8192), 16, 0, 0); } while (0)
; #define PG8_LDA(dst, b, h) do { _Pragma("unroll") for (int m = 0; m < 4; ++m) _Pragma("unroll") for (int k = 0; k < 2; ++k) dst[m][k] = *(const LAS bf16x8*)(lds + PG8_SA(b, h) + aoff + m * 2048 + k * 1024); } while (0)
; #define PG8_LDB(dst, b, h) do { _Pragma("unroll") for (int n = 0; n < 2; ++n) _Pragma("unroll") for (int k = 0; k < 2; ++k) dst[n][k] = *(const LAS bf16x8*)(lds + PG8_SB(b, h) + boff + n * 2048 + k * 1024); } while (0)
; #define PG8_MMA(ai, bj, At, Bt) do { __builtin_amdgcn_s_setprio(1); _Pragma("unroll") for (int m = 0; m < 4; ++m) _Pragma("unroll") for (int n = 0; n < 2; ++n) _Pragma("unroll") for (int k = 0; k < 2; ++k) \
;         acc[ai][bj][m][n] = __builtin_amdgcn_mfma_f32_16x16x32_bf16(Bt[n][k], At[m][k], acc[ai][bj][m][n], 0, 0, 0); __builtin_amdgcn_s_setprio(0); } while (0)
; #define PG8_WAIT_V(n) asm volatile("s_waitcnt vmcnt(" #n ")" ::: "memory")
; #define PG8_WAIT_L(n) asm volatile("s_waitcnt lgkmcnt(" #n ")" ::: "memory")
; #define PG8_BAR __builtin_amdgcn_s_barrier()
; #define PG8_SCHED __builtin_amdgcn_sched_barrier(0)
; template <class Epi, class Sched>
; DI void gemm_phase(LAS unsigned char* lds, const int K, const Sched& S, const Epi& E, const int wid) {
;     ...
;             PG8_WAIT_V(8); PG8_WAIT_L(0); PG8_BAR; PG8_MMA(1, 0, At, B0); PG8_MMA(1, 1, At, B1); PG8_BAR; PG8_SCHED;
;             PG8_LDB(B0, 1, 0); PG8_LDB(B1, 1, 1); PG8_SCHED; PG8_LDA(At, 1, 0); PG8_STAGE(PG8_SA(0, 1), a2 + hstep, voffA);
;             PG8_WAIT_V(8); PG8_WAIT_L(0); PG8_BAR; PG8_MMA(0, 0, At, B0); PG8_MMA(0, 1, At, B1); PG8_BAR; PG8_SCHED;
	v_mfma_f32_16x16x32_bf16 v[60:63], v[128:131], v[160:163], v[60:63]
	v_mfma_f32_16x16x32_bf16 v[56:59], v[136:139], v[160:163], v[56:59]
	v_mfma_f32_16x16x32_bf16 v[48:51], v[128:131], v[168:171], v[48:51]
	v_mfma_f32_16x16x32_bf16 v[40:43], v[136:139], v[168:171], v[40:43]
	v_mfma_f32_16x16x32_bf16 v[32:35], v[128:131], v[188:191], v[32:35]
	v_mfma_f32_16x16x32_bf16 v[24:27], v[136:139], v[188:191], v[24:27]
	v_mfma_f32_16x16x32_bf16 v[16:19], v[128:131], v[196:199], v[16:19]
	v_mfma_f32_16x16x32_bf16 v[8:11], v[136:139], v[196:199], v[8:11]
	v_mfma_f32_16x16x32_bf16 v[60:63], v[132:135], v[164:167], v[60:63]
	v_mfma_f32_16x16x32_bf16 v[56:59], v[140:143], v[164:167], v[56:59]
	v_mfma_f32_16x16x32_bf16 v[48:51], v[132:135], v[172:175], v[48:51]
	v_mfma_f32_16x16x32_bf16 v[40:43], v[140:143], v[172:175], v[40:43]
	v_mfma_f32_16x16x32_bf16 v[32:35], v[132:135], v[192:195], v[32:35]
	v_mfma_f32_16x16x32_bf16 v[24:27], v[140:143], v[192:195], v[24:27]
	v_mfma_f32_16x16x32_bf16 v[16:19], v[132:135], v[200:203], v[16:19]
	v_mfma_f32_16x16x32_bf16 v[8:11], v[140:143], v[200:203], v[8:11]
	v_mfma_f32_16x16x32_bf16 v[52:55], v[144:147], v[160:163], v[52:55]
	v_mfma_f32_16x16x32_bf16 v[44:47], v[152:155], v[160:163], v[44:47]
	v_mfma_f32_16x16x32_bf16 v[36:39], v[144:147], v[168:171], v[36:39]
	v_mfma_f32_16x16x32_bf16 v[28:31], v[152:155], v[168:171], v[28:31]
	v_mfma_f32_16x16x32_bf16 v[20:23], v[144:147], v[188:191], v[20:23]
	v_mfma_f32_16x16x32_bf16 v[12:15], v[152:155], v[188:191], v[12:15]
	v_mfma_f32_16x16x32_bf16 v[4:7], v[144:147], v[196:199], v[4:7]
	v_mfma_f32_16x16x32_bf16 v[0:3], v[152:155], v[196:199], v[0:3]
	v_mfma_f32_16x16x32_bf16 v[52:55], v[148:151], v[164:167], v[52:55]
	v_mfma_f32_16x16x32_bf16 v[44:47], v[156:159], v[164:167], v[44:47]
	v_mfma_f32_16x16x32_bf16 v[36:39], v[148:151], v[172:175], v[36:39]
	v_mfma_f32_16x16x32_bf16 v[28:31], v[156:159], v[172:175], v[28:31]
	v_mfma_f32_16x16x32_bf16 v[20:23], v[148:151], v[192:195], v[20:23]
	v_mfma_f32_16x16x32_bf16 v[12:15], v[156:159], v[192:195], v[12:15]
	v_mfma_f32_16x16x32_bf16 v[4:7], v[148:151], v[200:203], v[4:7]
	v_mfma_f32_16x16x32_bf16 v[0:3], v[156:159], v[200:203], v[0:3]
	s_barrier
	s_setprio 1
	s_add_i32 s96, 0, 0x18000
	s_add_i32 s90, 0, 0x1c000
	v_add_u32_e32 v140, s96, v207
	v_add_u32_e32 v156, s90, v207
	ds_read_b128 v[128:131], v140
	ds_read_b128 v[132:135], v140 offset:1024
	ds_read_b128 v[136:139], v140 offset:2048
	ds_read_b128 v[140:143], v140 offset:3072
	ds_read_b128 v[144:147], v156
	ds_read_b128 v[148:151], v156 offset:1024
	ds_read_b128 v[152:155], v156 offset:2048
	ds_read_b128 v[156:159], v156 offset:3072
	s_add_u32 s6, s6, 0x40000
	s_addc_u32 s7, s7, 0
	s_mov_b32 m0, s29
	v_lshl_add_u64 v[220:221], s[6:7], 0, v[176:177]
	ds_read_b128 v[160:163], v210 offset:32768
	ds_read_b128 v[164:167], v210 offset:33792
	ds_read_b128 v[168:171], v210 offset:34816
	ds_read_b128 v[172:175], v210 offset:35840
	ds_read_b128 v[188:191], v210 offset:36864
	ds_read_b128 v[192:195], v210 offset:37888
	ds_read_b128 v[196:199], v210 offset:38912
	ds_read_b128 v[200:203], v210 offset:39936
	global_load_lds_dwordx4 v[220:221], off
	v_lshl_add_u64 v[220:221], s[6:7], 0, v[180:181]
	s_mov_b32 m0, s97
	s_nop 0
	global_load_lds_dwordx4 v[220:221], off
	s_waitcnt vmcnt(8)
	s_waitcnt lgkmcnt(0)
	s_setprio 0
	s_barrier
	v_mfma_f32_16x16x32_bf16 v[124:127], v[128:131], v[160:163], v[124:127]
	v_mfma_f32_16x16x32_bf16 v[120:123], v[136:139], v[160:163], v[120:123]
	v_mfma_f32_16x16x32_bf16 v[108:111], v[128:131], v[168:171], v[108:111]
	v_mfma_f32_16x16x32_bf16 v[104:107], v[136:139], v[168:171], v[104:107]
	v_mfma_f32_16x16x32_bf16 v[96:99], v[128:131], v[188:191], v[96:99]
	v_mfma_f32_16x16x32_bf16 v[88:91], v[136:139], v[188:191], v[88:91]
	v_mfma_f32_16x16x32_bf16 v[80:83], v[128:131], v[196:199], v[80:83]
	v_mfma_f32_16x16x32_bf16 v[72:75], v[136:139], v[196:199], v[72:75]
	v_mfma_f32_16x16x32_bf16 v[124:127], v[132:135], v[164:167], v[124:127]
	v_mfma_f32_16x16x32_bf16 v[120:123], v[140:143], v[164:167], v[120:123]
	v_mfma_f32_16x16x32_bf16 v[108:111], v[132:135], v[172:175], v[108:111]
	v_mfma_f32_16x16x32_bf16 v[104:107], v[140:143], v[172:175], v[104:107]
	v_mfma_f32_16x16x32_bf16 v[96:99], v[132:135], v[192:195], v[96:99]
	v_mfma_f32_16x16x32_bf16 v[88:91], v[140:143], v[192:195], v[88:91]
	v_mfma_f32_16x16x32_bf16 v[80:83], v[132:135], v[200:203], v[80:83]
	v_mfma_f32_16x16x32_bf16 v[72:75], v[140:143], v[200:203], v[72:75]
	v_mfma_f32_16x16x32_bf16 v[116:119], v[144:147], v[160:163], v[116:119]
	v_mfma_f32_16x16x32_bf16 v[112:115], v[152:155], v[160:163], v[112:115]
	v_mfma_f32_16x16x32_bf16 v[100:103], v[144:147], v[168:171], v[100:103]
	v_mfma_f32_16x16x32_bf16 v[92:95], v[152:155], v[168:171], v[92:95]
	v_mfma_f32_16x16x32_bf16 v[84:87], v[144:147], v[188:191], v[84:87]
	v_mfma_f32_16x16x32_bf16 v[76:79], v[152:155], v[188:191], v[76:79]
	v_mfma_f32_16x16x32_bf16 v[68:71], v[144:147], v[196:199], v[68:71]
	v_mfma_f32_16x16x32_bf16 v[64:67], v[152:155], v[196:199], v[64:67]
	v_mfma_f32_16x16x32_bf16 v[116:119], v[148:151], v[164:167], v[116:119]
	v_mfma_f32_16x16x32_bf16 v[112:115], v[156:159], v[164:167], v[112:115]
	v_mfma_f32_16x16x32_bf16 v[100:103], v[148:151], v[172:175], v[100:103]
	v_mfma_f32_16x16x32_bf16 v[92:95], v[156:159], v[172:175], v[92:95]
	v_mfma_f32_16x16x32_bf16 v[84:87], v[148:151], v[192:195], v[84:87]
	v_mfma_f32_16x16x32_bf16 v[76:79], v[156:159], v[192:195], v[76:79]
	v_mfma_f32_16x16x32_bf16 v[68:71], v[148:151], v[200:203], v[68:71]
	v_mfma_f32_16x16x32_bf16 v[64:67], v[156:159], v[200:203], v[64:67]
	s_barrier
; #define PG8_STAGE(bufoff, gbase, voff) do { _Pragma("unroll") for (int _i = 0; _i < 2; ++_i) \
;         __builtin_amdgcn_global_load_lds((const unsigned*)((const char*)(gbase) + (voff)[_i]), (LAS unsigned*)(lds + (bufoff) + ldsw + _i * 8192), 16, 0, 0); } while (0)
; #define PG8_LDA(dst, b, h) do { _Pragma("unroll") for (int m = 0; m < 4; ++m) _Pragma("unroll") for (int k = 0; k < 2; ++k) dst[m][k] = *(const LAS bf16x8*)(lds + PG8_SA(b, h) + aoff + m * 2048 + k * 1024); } while (0)
; #define PG8_MMA(ai, bj, At, Bt) do { __builtin_amdgcn_s_setprio(1); _Pragma("unroll") for (int m = 0; m < 4; ++m) _Pragma("unroll") for (int n = 0; n < 2; ++n) _Pragma("unroll") for (int k = 0; k < 2; ++k) \
;         acc[ai][bj][m][n] = __builtin_amdgcn_mfma_f32_16x16x32_bf16(Bt[n][k], At[m][k], acc[ai][bj][m][n], 0, 0, 0); __builtin_amdgcn_s_setprio(0); } while (0)
; #define PG8_WAIT_V(n) asm volatile("s_waitcnt vmcnt(" #n ")" ::: "memory")
; #define PG8_WAIT_L(n) asm volatile("s_waitcnt lgkmcnt(" #n ")" ::: "memory")
; #define PG8_BAR __builtin_amdgcn_s_barrier()
; #define PG8_SCHED __builtin_amdgcn_sched_barrier(0)
; template <class Epi, class Sched>
; DI void gemm_phase(LAS unsigned char* lds, const int K, const Sched& S, const Epi& E, const int wid) {
;     ...
;             PG8_LDA(At, 1, 1); PG8_STAGE(PG8_SB(1, 0), b3, voffB); PG8_STAGE(PG8_SB(1, 1), b3 + hstep, voffB); PG8_STAGE(PG8_SA(1, 0), a3, voffA);
;             PG8_WAIT_V(8); PG8_WAIT_L(0); PG8_BAR; PG8_MMA(1, 0, At, B0); PG8_MMA(1, 1, At, B1); PG8_BAR; PG8_SCHED;
;         }
	s_setprio 1
	s_add_i32 s94, s96, s95
	s_add_i32 s84, s94, 0x2000
	v_lshl_add_u64 v[212:213], v[212:213], 0, s[34:35]
	s_mov_b32 m0, s94
	s_add_u32 s4, s4, 0x40080
	ds_read_b128 v[160:163], v210 offset:49152
	ds_read_b128 v[164:167], v210 offset:50176
	ds_read_b128 v[168:171], v210 offset:51200
	ds_read_b128 v[172:175], v210 offset:52224
	ds_read_b128 v[188:191], v210 offset:53248
	ds_read_b128 v[192:195], v210 offset:54272
	ds_read_b128 v[196:199], v210 offset:55296
	ds_read_b128 v[200:203], v210 offset:56320
	global_load_lds_dwordx4 v[212:213], off
	v_lshl_add_u64 v[212:213], v[214:215], 0, s[34:35]
	s_mov_b32 m0, s84
	s_addc_u32 s5, s5, 0
	s_add_i32 s86, s90, s95
	global_load_lds_dwordx4 v[212:213], off
	v_lshl_add_u64 v[212:213], s[4:5], 0, v[178:179]
	s_mov_b32 m0, s86
	s_add_i32 s28, s86, 0x2000
	global_load_lds_dwordx4 v[212:213], off
	v_lshl_add_u64 v[212:213], s[4:5], 0, v[182:183]
	s_mov_b32 m0, s28
	s_nop 0
	global_load_lds_dwordx4 v[212:213], off
	v_lshl_add_u64 v[212:213], v[216:217], 0, s[34:35]
	s_mov_b32 m0, s91
	s_nop 0
	global_load_lds_dwordx4 v[212:213], off
	v_lshl_add_u64 v[212:213], v[218:219], 0, s[34:35]
	s_mov_b32 m0, s88
	s_nop 0
	global_load_lds_dwordx4 v[212:213], off
	s_waitcnt vmcnt(8)
	s_waitcnt lgkmcnt(0)
	s_setprio 0
	s_barrier
	v_mfma_f32_16x16x32_bf16 v[60:63], v[128:131], v[160:163], v[60:63]
	v_mfma_f32_16x16x32_bf16 v[56:59], v[136:139], v[160:163], v[56:59]
	v_mfma_f32_16x16x32_bf16 v[48:51], v[128:131], v[168:171], v[48:51]
	v_mfma_f32_16x16x32_bf16 v[40:43], v[136:139], v[168:171], v[40:43]
	v_mfma_f32_16x16x32_bf16 v[32:35], v[128:131], v[188:191], v[32:35]
	v_mfma_f32_16x16x32_bf16 v[24:27], v[136:139], v[188:191], v[24:27]
	v_mfma_f32_16x16x32_bf16 v[16:19], v[128:131], v[196:199], v[16:19]
	v_mfma_f32_16x16x32_bf16 v[8:11], v[136:139], v[196:199], v[8:11]
	v_mfma_f32_16x16x32_bf16 v[60:63], v[132:135], v[164:167], v[60:63]
	v_mfma_f32_16x16x32_bf16 v[56:59], v[140:143], v[164:167], v[56:59]
	v_mfma_f32_16x16x32_bf16 v[48:51], v[132:135], v[172:175], v[48:51]
	v_mfma_f32_16x16x32_bf16 v[40:43], v[140:143], v[172:175], v[40:43]
	v_mfma_f32_16x16x32_bf16 v[32:35], v[132:135], v[192:195], v[32:35]
	v_mfma_f32_16x16x32_bf16 v[24:27], v[140:143], v[192:195], v[24:27]
	v_mfma_f32_16x16x32_bf16 v[16:19], v[132:135], v[200:203], v[16:19]
	v_mfma_f32_16x16x32_bf16 v[8:11], v[140:143], v[200:203], v[8:11]
	v_mfma_f32_16x16x32_bf16 v[52:55], v[144:147], v[160:163], v[52:55]
	v_mfma_f32_16x16x32_bf16 v[44:47], v[152:155], v[160:163], v[44:47]
	v_mfma_f32_16x16x32_bf16 v[36:39], v[144:147], v[168:171], v[36:39]
	v_mfma_f32_16x16x32_bf16 v[28:31], v[152:155], v[168:171], v[28:31]
	v_mfma_f32_16x16x32_bf16 v[20:23], v[144:147], v[188:191], v[20:23]
	v_mfma_f32_16x16x32_bf16 v[12:15], v[152:155], v[188:191], v[12:15]
	v_mfma_f32_16x16x32_bf16 v[4:7], v[144:147], v[196:199], v[4:7]
	v_mfma_f32_16x16x32_bf16 v[0:3], v[152:155], v[196:199], v[0:3]
	v_mfma_f32_16x16x32_bf16 v[52:55], v[148:151], v[164:167], v[52:55]
	v_mfma_f32_16x16x32_bf16 v[44:47], v[156:159], v[164:167], v[44:47]
	v_mfma_f32_16x16x32_bf16 v[36:39], v[148:151], v[172:175], v[36:39]
	v_mfma_f32_16x16x32_bf16 v[28:31], v[156:159], v[172:175], v[28:31]
	v_mfma_f32_16x16x32_bf16 v[20:23], v[148:151], v[192:195], v[20:23]
	v_mfma_f32_16x16x32_bf16 v[12:15], v[156:159], v[192:195], v[12:15]
	v_mfma_f32_16x16x32_bf16 v[4:7], v[148:151], v[200:203], v[4:7]
	v_mfma_f32_16x16x32_bf16 v[0:3], v[156:159], v[200:203], v[0:3]
	s_barrier
	s_setprio 1
	s_add_u32 s56, s56, 0x100
	s_addc_u32 s57, s57, 0
	s_add_u32 s45, s45, 0x100
	s_addc_u32 s47, s47, 0
	s_cmp_ge_u32 s49, s43
	s_mov_b32 s4, s49
	s_cbranch_scc0 .LBB0_539
	v_readlane_b32 s4, v249, 25
	v_readlane_b32 s5, v249, 26
	s_and_b64 vcc, exec, s[4:5]
	s_cbranch_vccz .LBB0_542
	s_barrier

; #define PG8_STAGE(bufoff, gbase, voff) do { _Pragma("unroll") for (int _i = 0; _i < 2; ++_i) \
;         __builtin_amdgcn_global_load_lds((const unsigned*)((const char*)(gbase) + (voff)[_i]), (LAS unsigned*)(lds + (bufoff) + ldsw + _i * 8192), 16, 0, 0); } while (0)
; #define PG8_LDA(dst, b, h) do { _Pragma("unroll") for (int m = 0; m < 4; ++m) _Pragma("unroll") for (int k = 0; k < 2; ++k) dst[m][k] = *(const LAS bf16x8*)(lds + PG8_SA(b, h) + aoff + m * 2048 + k * 1024); } while (0)
; #define PG8_LDB(dst, b, h) do { _Pragma("unroll") for (int n = 0; n < 2; ++n) _Pragma("unroll") for (int k = 0; k < 2; ++k) dst[n][k] = *(const LAS bf16x8*)(lds + PG8_SB(b, h) + boff + n * 2048 + k * 1024); } while (0)
; #define PG8_MMA(ai, bj, At, Bt) do { __builtin_amdgcn_s_setprio(1); _Pragma("unroll") for (int m = 0; m < 4; ++m) _Pragma("unroll") for (int n = 0; n < 2; ++n) _Pragma("unroll") for (int k = 0; k < 2; ++k) \
;         acc[ai][bj][m][n] = __builtin_amdgcn_mfma_f32_16x16x32_bf16(Bt[n][k], At[m][k], acc[ai][bj][m][n], 0, 0, 0); __builtin_amdgcn_s_setprio(0); } while (0)
; #define PG8_WAIT_V(n) asm volatile("s_waitcnt vmcnt(" #n ")" ::: "memory")
; #define PG8_WAIT_L(n) asm volatile("s_waitcnt lgkmcnt(" #n ")" ::: "memory")
; #define PG8_BAR __builtin_amdgcn_s_barrier()
; #define PG8_SCHED __builtin_amdgcn_sched_barrier(0)
; template <class Epi, class Sched>
; DI void gemm_phase(LAS unsigned char* lds, const int K, const Sched& S, const Epi& E, const int wid) {
;     ...
;             const bool last = (t == nt - 2);
;             const char* a1 = cA + (size_t)(t + 1) * kstep;
;             const char* a2 = last ? nA : cA + (size_t)(t + 2) * kstep; const char* b2 = last ? nB : cB + (size_t)(t + 2) * kstep;
;             const char* a3 = a2 + kstep; const char* b3 = b2 + kstep;
;             if (last && has_next) S.a_ready(nxt);
;             PG8_LDB(B0, 0, 0); PG8_LDB(B1, 0, 1); PG8_SCHED; PG8_LDA(At, 0, 0); PG8_STAGE(PG8_SA(1, 1), a1 + hstep, voffA);
;             PG8_WAIT_V(8); PG8_WAIT_L(0); PG8_BAR; PG8_MMA(0, 0, At, B0); PG8_MMA(0, 1, At, B1); PG8_BAR; PG8_SCHED;
;             PG8_LDA(At, 0, 1); PG8_STAGE(PG8_SB(0, 0), b2, voffB); PG8_STAGE(PG8_SB(0, 1), b2 + hstep, voffB); PG8_STAGE(PG8_SA(0, 0), a2, voffA);
;             PG8_WAIT_V(8); PG8_WAIT_L(0); PG8_BAR; PG8_MMA(1, 0, At, B0); PG8_MMA(1, 1, At, B1); PG8_BAR; PG8_SCHED;
.LBB0_706:
	s_or_b32 s44, s6, 1
	s_lshl_b64 s[20:21], s[44:45], 7
	s_add_u32 s15, s62, s20
	s_addc_u32 s24, s63, s21
	s_add_i32 s44, s6, 2
	v_add_u32_e32 v140, s70, v208
	v_add_u32_e32 v156, s2, v208
	s_lshl_b64 s[20:21], s[44:45], 7
	s_waitcnt lgkmcnt(0)
	ds_read_b128 v[128:131], v140
	ds_read_b128 v[132:135], v140 offset:1024
	ds_read_b128 v[136:139], v140 offset:2048
	ds_read_b128 v[140:143], v140 offset:3072
	ds_read_b128 v[144:147], v156
	ds_read_b128 v[148:151], v156 offset:1024
	ds_read_b128 v[152:155], v156 offset:2048
	ds_read_b128 v[156:159], v156 offset:3072
	s_add_u32 s25, s62, s20
	s_addc_u32 s39, s63, s21
	s_and_b64 s[6:7], s[4:5], exec
	s_cselect_b32 s7, s53, s39
	s_cselect_b32 s6, s52, s25
	s_add_u32 s20, s60, s20
	s_addc_u32 s21, s61, s21
	s_and_b64 s[4:5], s[4:5], exec
	s_cselect_b32 s5, s55, s21
	s_cselect_b32 s4, s54, s20
	s_add_u32 s20, s15, 0x80000
	s_addc_u32 s21, s24, 0
	s_mov_b32 m0, s89
	v_lshl_add_u64 v[200:201], s[20:21], 0, v[184:185]
	ds_read_b128 v[160:163], v210
	ds_read_b128 v[164:167], v210 offset:1024
	ds_read_b128 v[168:171], v210 offset:2048
	ds_read_b128 v[172:175], v210 offset:3072
	ds_read_b128 v[176:179], v210 offset:4096
	ds_read_b128 v[180:183], v210 offset:5120
	ds_read_b128 v[192:195], v210 offset:6144
	ds_read_b128 v[196:199], v210 offset:7168
	global_load_lds_dwordx4 v[200:201], off
	v_lshl_add_u64 v[200:201], s[20:21], 0, v[188:189]
	s_mov_b32 m0, s26
	s_nop 0
	global_load_lds_dwordx4 v[200:201], off
	s_waitcnt vmcnt(8)
	s_waitcnt lgkmcnt(0)
	s_setprio 0
	s_barrier
	v_mfma_f32_16x16x32_bf16 v[124:127], v[128:131], v[160:163], v[124:127]
	v_mfma_f32_16x16x32_bf16 v[120:123], v[136:139], v[160:163], v[120:123]
	v_mfma_f32_16x16x32_bf16 v[116:119], v[128:131], v[168:171], v[116:119]
	v_mfma_f32_16x16x32_bf16 v[112:115], v[136:139], v[168:171], v[112:115]
	v_mfma_f32_16x16x32_bf16 v[100:103], v[128:131], v[176:179], v[100:103]
	v_mfma_f32_16x16x32_bf16 v[96:99], v[136:139], v[176:179], v[96:99]
	v_mfma_f32_16x16x32_bf16 v[84:87], v[128:131], v[192:195], v[84:87]
	v_mfma_f32_16x16x32_bf16 v[80:83], v[136:139], v[192:195], v[80:83]
	v_mfma_f32_16x16x32_bf16 v[124:127], v[132:135], v[164:167], v[124:127]
	v_mfma_f32_16x16x32_bf16 v[120:123], v[140:143], v[164:167], v[120:123]
	v_mfma_f32_16x16x32_bf16 v[116:119], v[132:135], v[172:175], v[116:119]
	v_mfma_f32_16x16x32_bf16 v[112:115], v[140:143], v[172:175], v[112:115]
	v_mfma_f32_16x16x32_bf16 v[100:103], v[132:135], v[180:183], v[100:103]
	v_mfma_f32_16x16x32_bf16 v[96:99], v[140:143], v[180:183], v[96:99]
	v_mfma_f32_16x16x32_bf16 v[84:87], v[132:135], v[196:199], v[84:87]
	v_mfma_f32_16x16x32_bf16 v[80:83], v[140:143], v[196:199], v[80:83]
	v_mfma_f32_16x16x32_bf16 v[108:111], v[144:147], v[160:163], v[108:111]
	v_mfma_f32_16x16x32_bf16 v[104:107], v[152:155], v[160:163], v[104:107]
	v_mfma_f32_16x16x32_bf16 v[92:95], v[144:147], v[168:171], v[92:95]
	v_mfma_f32_16x16x32_bf16 v[88:91], v[152:155], v[168:171], v[88:91]
	v_mfma_f32_16x16x32_bf16 v[76:79], v[144:147], v[176:179], v[76:79]
	v_mfma_f32_16x16x32_bf16 v[72:75], v[152:155], v[176:179], v[72:75]
	v_mfma_f32_16x16x32_bf16 v[68:71], v[144:147], v[192:195], v[68:71]
	v_mfma_f32_16x16x32_bf16 v[64:67], v[152:155], v[192:195], v[64:67]
	v_mfma_f32_16x16x32_bf16 v[108:111], v[148:151], v[164:167], v[108:111]
	v_mfma_f32_16x16x32_bf16 v[104:107], v[156:159], v[164:167], v[104:107]
	v_mfma_f32_16x16x32_bf16 v[92:95], v[148:151], v[172:175], v[92:95]
	v_mfma_f32_16x16x32_bf16 v[88:91], v[156:159], v[172:175], v[88:91]
	v_mfma_f32_16x16x32_bf16 v[76:79], v[148:151], v[180:183], v[76:79]
	v_mfma_f32_16x16x32_bf16 v[72:75], v[156:159], v[180:183], v[72:75]
	v_mfma_f32_16x16x32_bf16 v[68:71], v[148:151], v[196:199], v[68:71]
	v_mfma_f32_16x16x32_bf16 v[64:67], v[156:159], v[196:199], v[64:67]
	s_barrier
	s_setprio 1
	s_mov_b32 m0, s27
	v_lshl_add_u64 v[200:201], s[4:5], 0, v[186:187]
	s_add_u32 s20, s4, 0x80000
	ds_read_b128 v[160:163], v210 offset:16384
	ds_read_b128 v[164:167], v210 offset:17408
	ds_read_b128 v[168:171], v210 offset:18432
	ds_read_b128 v[172:175], v210 offset:19456
	ds_read_b128 v[176:179], v210 offset:20480
	ds_read_b128 v[180:183], v210 offset:21504
	ds_read_b128 v[192:195], v210 offset:22528
	ds_read_b128 v[196:199], v210 offset:23552
	global_load_lds_dwordx4 v[200:201], off
	v_lshl_add_u64 v[202:203], s[4:5], 0, v[190:191]
	s_mov_b32 m0, s22
	s_addc_u32 s21, s5, 0
	global_load_lds_dwordx4 v[202:203], off
	v_lshl_add_u64 v[204:205], s[20:21], 0, v[186:187]
	s_mov_b32 m0, s23
	v_lshl_add_u64 v[212:213], s[6:7], 0, v[188:189]
	global_load_lds_dwordx4 v[204:205], off
	v_lshl_add_u64 v[204:205], s[20:21], 0, v[190:191]
	s_mov_b32 m0, s87
	s_nop 0
	global_load_lds_dwordx4 v[204:205], off
	v_lshl_add_u64 v[204:205], s[6:7], 0, v[184:185]
	s_mov_b32 m0, s85
	s_nop 0
	global_load_lds_dwordx4 v[204:205], off
	s_mov_b32 m0, s33
	s_nop 0
	global_load_lds_dwordx4 v[212:213], off
	s_waitcnt vmcnt(8)
	s_waitcnt lgkmcnt(0)
	s_setprio 0
	s_barrier
; #define PG8_STAGE(bufoff, gbase, voff) do { _Pragma("unroll") for (int _i = 0; _i < 2; ++_i) \
;         __builtin_amdgcn_global_load_lds((const unsigned*)((const char*)(gbase) + (voff)[_i]), (LAS unsigned*)(lds + (bufoff) + ldsw + _i * 8192), 16, 0, 0); } while (0)
; #define PG8_LDA(dst, b, h) do { _Pragma("unroll") for (int m = 0; m < 4; ++m) _Pragma("unroll") for (int k = 0; k < 2; ++k) dst[m][k] = *(const LAS bf16x8*)(lds + PG8_SA(b, h) + aoff + m * 2048 + k * 1024); } while (0)
; #define PG8_LDB(dst, b, h) do { _Pragma("unroll") for (int n = 0; n < 2; ++n) _Pragma("unroll") for (int k = 0; k < 2; ++k) dst[n][k] = *(const LAS bf16x8*)(lds + PG8_SB(b, h) + boff + n * 2048 + k * 1024); } while (0)
; #define PG8_MMA(ai, bj, At, Bt) do { __builtin_amdgcn_s_setprio(1); _Pragma("unroll") for (int m = 0; m < 4; ++m) _Pragma("unroll") for (int n = 0; n < 2; ++n) _Pragma("unroll") for (int k = 0; k < 2; ++k) \
;         acc[ai][bj][m][n] = __builtin_amdgcn_mfma_f32_16x16x32_bf16(Bt[n][k], At[m][k], acc[ai][bj][m][n], 0, 0, 0); __builtin_amdgcn_s_setprio(0); } while (0)
; #define PG8_WAIT_V(n) asm volatile("s_waitcnt vmcnt(" #n ")" ::: "memory")
; #define PG8_WAIT_L(n) asm volatile("s_waitcnt lgkmcnt(" #n ")" ::: "memory")
; #define PG8_BAR __builtin_amdgcn_s_barrier()
; #define PG8_SCHED __builtin_amdgcn_sched_barrier(0)
; template <class Epi, class Sched>
; DI void gemm_phase(LAS unsigned char* lds, const int K, const Sched& S, const Epi& E, const int wid) {
;     ...
;             PG8_WAIT_V(8); PG8_WAIT_L(0); PG8_BAR; PG8_MMA(1, 0, At, B0); PG8_MMA(1, 1, At, B1); PG8_BAR; PG8_SCHED;
;             PG8_LDB(B0, 1, 0); PG8_LDB(B1, 1, 1); PG8_SCHED; PG8_LDA(At, 1, 0); PG8_STAGE(PG8_SA(0, 1), a2 + hstep, voffA);
;             PG8_WAIT_V(8); PG8_WAIT_L(0); PG8_BAR; PG8_MMA(0, 0, At, B0); PG8_MMA(0, 1, At, B1); PG8_BAR; PG8_SCHED;
	v_mfma_f32_16x16x32_bf16 v[60:63], v[128:131], v[160:163], v[60:63]
	v_mfma_f32_16x16x32_bf16 v[56:59], v[136:139], v[160:163], v[56:59]
	v_mfma_f32_16x16x32_bf16 v[52:55], v[128:131], v[168:171], v[52:55]
	v_mfma_f32_16x16x32_bf16 v[48:51], v[136:139], v[168:171], v[48:51]
	v_mfma_f32_16x16x32_bf16 v[36:39], v[128:131], v[176:179], v[36:39]
	v_mfma_f32_16x16x32_bf16 v[32:35], v[136:139], v[176:179], v[32:35]
	v_mfma_f32_16x16x32_bf16 v[20:23], v[128:131], v[192:195], v[20:23]
	v_mfma_f32_16x16x32_bf16 v[16:19], v[136:139], v[192:195], v[16:19]
	v_mfma_f32_16x16x32_bf16 v[60:63], v[132:135], v[164:167], v[60:63]
	v_mfma_f32_16x16x32_bf16 v[56:59], v[140:143], v[164:167], v[56:59]
	v_mfma_f32_16x16x32_bf16 v[52:55], v[132:135], v[172:175], v[52:55]
	v_mfma_f32_16x16x32_bf16 v[48:51], v[140:143], v[172:175], v[48:51]
	v_mfma_f32_16x16x32_bf16 v[36:39], v[132:135], v[180:183], v[36:39]
	v_mfma_f32_16x16x32_bf16 v[32:35], v[140:143], v[180:183], v[32:35]
	v_mfma_f32_16x16x32_bf16 v[20:23], v[132:135], v[196:199], v[20:23]
	v_mfma_f32_16x16x32_bf16 v[16:19], v[140:143], v[196:199], v[16:19]
	v_mfma_f32_16x16x32_bf16 v[44:47], v[144:147], v[160:163], v[44:47]
	v_mfma_f32_16x16x32_bf16 v[40:43], v[152:155], v[160:163], v[40:43]
	v_mfma_f32_16x16x32_bf16 v[28:31], v[144:147], v[168:171], v[28:31]
	v_mfma_f32_16x16x32_bf16 v[24:27], v[152:155], v[168:171], v[24:27]
	v_mfma_f32_16x16x32_bf16 v[12:15], v[144:147], v[176:179], v[12:15]
	v_mfma_f32_16x16x32_bf16 v[8:11], v[152:155], v[176:179], v[8:11]
	v_mfma_f32_16x16x32_bf16 v[4:7], v[144:147], v[192:195], v[4:7]
	v_mfma_f32_16x16x32_bf16 v[0:3], v[152:155], v[192:195], v[0:3]
	v_mfma_f32_16x16x32_bf16 v[44:47], v[148:151], v[164:167], v[44:47]
	v_mfma_f32_16x16x32_bf16 v[40:43], v[156:159], v[164:167], v[40:43]
	v_mfma_f32_16x16x32_bf16 v[28:31], v[148:151], v[172:175], v[28:31]
	v_mfma_f32_16x16x32_bf16 v[24:27], v[156:159], v[172:175], v[24:27]
	v_mfma_f32_16x16x32_bf16 v[12:15], v[148:151], v[180:183], v[12:15]
	v_mfma_f32_16x16x32_bf16 v[8:11], v[156:159], v[180:183], v[8:11]
	v_mfma_f32_16x16x32_bf16 v[4:7], v[148:151], v[196:199], v[4:7]
	v_mfma_f32_16x16x32_bf16 v[0:3], v[156:159], v[196:199], v[0:3]
	s_barrier
	s_setprio 1
	v_add_u32_e32 v140, s96, v208
	v_add_u32_e32 v156, s90, v208
	ds_read_b128 v[128:131], v140
	ds_read_b128 v[132:135], v140 offset:1024
	ds_read_b128 v[136:139], v140 offset:2048
	ds_read_b128 v[140:143], v140 offset:3072
	ds_read_b128 v[144:147], v156
	ds_read_b128 v[148:151], v156 offset:1024
	ds_read_b128 v[152:155], v156 offset:2048
	ds_read_b128 v[156:159], v156 offset:3072
	s_add_u32 s6, s6, 0x80000
	s_addc_u32 s7, s7, 0
	s_mov_b32 m0, s29
	v_lshl_add_u64 v[214:215], s[6:7], 0, v[184:185]
	ds_read_b128 v[160:163], v210 offset:32768
	ds_read_b128 v[164:167], v210 offset:33792
	ds_read_b128 v[168:171], v210 offset:34816
	ds_read_b128 v[172:175], v210 offset:35840
	ds_read_b128 v[176:179], v210 offset:36864
	ds_read_b128 v[180:183], v210 offset:37888
	ds_read_b128 v[192:195], v210 offset:38912
	ds_read_b128 v[196:199], v210 offset:39936
	global_load_lds_dwordx4 v[214:215], off
	v_lshl_add_u64 v[214:215], s[6:7], 0, v[188:189]
	s_mov_b32 m0, s97
	s_nop 0
	global_load_lds_dwordx4 v[214:215], off
	s_waitcnt vmcnt(8)
	s_waitcnt lgkmcnt(0)
	s_setprio 0
	s_barrier
	v_mfma_f32_16x16x32_bf16 v[124:127], v[128:131], v[160:163], v[124:127]
	v_mfma_f32_16x16x32_bf16 v[120:123], v[136:139], v[160:163], v[120:123]
	v_mfma_f32_16x16x32_bf16 v[116:119], v[128:131], v[168:171], v[116:119]
	v_mfma_f32_16x16x32_bf16 v[112:115], v[136:139], v[168:171], v[112:115]
	v_mfma_f32_16x16x32_bf16 v[100:103], v[128:131], v[176:179], v[100:103]
	v_mfma_f32_16x16x32_bf16 v[96:99], v[136:139], v[176:179], v[96:99]
	v_mfma_f32_16x16x32_bf16 v[84:87], v[128:131], v[192:195], v[84:87]
	v_mfma_f32_16x16x32_bf16 v[80:83], v[136:139], v[192:195], v[80:83]
	v_mfma_f32_16x16x32_bf16 v[124:127], v[132:135], v[164:167], v[124:127]
	v_mfma_f32_16x16x32_bf16 v[120:123], v[140:143], v[164:167], v[120:123]
	v_mfma_f32_16x16x32_bf16 v[116:119], v[132:135], v[172:175], v[116:119]
	v_mfma_f32_16x16x32_bf16 v[112:115], v[140:143], v[172:175], v[112:115]
	v_mfma_f32_16x16x32_bf16 v[100:103], v[132:135], v[180:183], v[100:103]
	v_mfma_f32_16x16x32_bf16 v[96:99], v[140:143], v[180:183], v[96:99]
	v_mfma_f32_16x16x32_bf16 v[84:87], v[132:135], v[196:199], v[84:87]
	v_mfma_f32_16x16x32_bf16 v[80:83], v[140:143], v[196:199], v[80:83]
	v_mfma_f32_16x16x32_bf16 v[108:111], v[144:147], v[160:163], v[108:111]
	v_mfma_f32_16x16x32_bf16 v[104:107], v[152:155], v[160:163], v[104:107]
	v_mfma_f32_16x16x32_bf16 v[92:95], v[144:147], v[168:171], v[92:95]
	v_mfma_f32_16x16x32_bf16 v[88:91], v[152:155], v[168:171], v[88:91]
	v_mfma_f32_16x16x32_bf16 v[76:79], v[144:147], v[176:179], v[76:79]
	v_mfma_f32_16x16x32_bf16 v[72:75], v[152:155], v[176:179], v[72:75]
	v_mfma_f32_16x16x32_bf16 v[68:71], v[144:147], v[192:195], v[68:71]
	v_mfma_f32_16x16x32_bf16 v[64:67], v[152:155], v[192:195], v[64:67]
	v_mfma_f32_16x16x32_bf16 v[108:111], v[148:151], v[164:167], v[108:111]
	v_mfma_f32_16x16x32_bf16 v[104:107], v[156:159], v[164:167], v[104:107]
	v_mfma_f32_16x16x32_bf16 v[92:95], v[148:151], v[172:175], v[92:95]
	v_mfma_f32_16x16x32_bf16 v[88:91], v[156:159], v[172:175], v[88:91]
	v_mfma_f32_16x16x32_bf16 v[76:79], v[148:151], v[180:183], v[76:79]
	v_mfma_f32_16x16x32_bf16 v[72:75], v[156:159], v[180:183], v[72:75]
	v_mfma_f32_16x16x32_bf16 v[68:71], v[148:151], v[196:199], v[68:71]
	v_mfma_f32_16x16x32_bf16 v[64:67], v[156:159], v[196:199], v[64:67]
	s_barrier
; #define PG8_STAGE(bufoff, gbase, voff) do { _Pragma("unroll") for (int _i = 0; _i < 2; ++_i) \
;         __builtin_amdgcn_global_load_lds((const unsigned*)((const char*)(gbase) + (voff)[_i]), (LAS unsigned*)(lds + (bufoff) + ldsw + _i * 8192), 16, 0, 0); } while (0)
; #define PG8_LDA(dst, b, h) do { _Pragma("unroll") for (int m = 0; m < 4; ++m) _Pragma("unroll") for (int k = 0; k < 2; ++k) dst[m][k] = *(const LAS bf16x8*)(lds + PG8_SA(b, h) + aoff + m * 2048 + k * 1024); } while (0)
; #define PG8_MMA(ai, bj, At, Bt) do { __builtin_amdgcn_s_setprio(1); _Pragma("unroll") for (int m = 0; m < 4; ++m) _Pragma("unroll") for (int n = 0; n < 2; ++n) _Pragma("unroll") for (int k = 0; k < 2; ++k) \
;         acc[ai][bj][m][n] = __builtin_amdgcn_mfma_f32_16x16x32_bf16(Bt[n][k], At[m][k], acc[ai][bj][m][n], 0, 0, 0); __builtin_amdgcn_s_setprio(0); } while (0)
; #define PG8_WAIT_V(n) asm volatile("s_waitcnt vmcnt(" #n ")" ::: "memory")
; #define PG8_WAIT_L(n) asm volatile("s_waitcnt lgkmcnt(" #n ")" ::: "memory")
; #define PG8_BAR __builtin_amdgcn_s_barrier()
; #define PG8_SCHED __builtin_amdgcn_sched_barrier(0)
; template <class Epi, class Sched>
; DI void gemm_phase(LAS unsigned char* lds, const int K, const Sched& S, const Epi& E, const int wid) {
;     ...
;             PG8_LDA(At, 1, 1); PG8_STAGE(PG8_SB(1, 0), b3, voffB); PG8_STAGE(PG8_SB(1, 1), b3 + hstep, voffB); PG8_STAGE(PG8_SA(1, 0), a3, voffA);
;             PG8_WAIT_V(8); PG8_WAIT_L(0); PG8_BAR; PG8_MMA(1, 0, At, B0); PG8_MMA(1, 1, At, B1); PG8_BAR; PG8_SCHED;
;         }
	s_setprio 1
	s_mov_b32 m0, s94
	v_lshl_add_u64 v[200:201], v[200:201], 0, s[46:47]
	s_add_u32 s4, s4, 0x80080
	ds_read_b128 v[160:163], v210 offset:49152
	ds_read_b128 v[164:167], v210 offset:50176
	ds_read_b128 v[168:171], v210 offset:51200
	ds_read_b128 v[172:175], v210 offset:52224
	ds_read_b128 v[176:179], v210 offset:53248
	ds_read_b128 v[180:183], v210 offset:54272
	ds_read_b128 v[192:195], v210 offset:55296
	ds_read_b128 v[196:199], v210 offset:56320
	global_load_lds_dwordx4 v[200:201], off
	v_lshl_add_u64 v[200:201], v[202:203], 0, s[46:47]
	s_mov_b32 m0, s84
	s_addc_u32 s5, s5, 0
	global_load_lds_dwordx4 v[200:201], off
	v_lshl_add_u64 v[200:201], s[4:5], 0, v[186:187]
	s_mov_b32 m0, s86
	s_nop 0
	global_load_lds_dwordx4 v[200:201], off
	v_lshl_add_u64 v[200:201], s[4:5], 0, v[190:191]
	s_mov_b32 m0, s28
	s_nop 0
	global_load_lds_dwordx4 v[200:201], off
	v_lshl_add_u64 v[200:201], v[204:205], 0, s[46:47]
	s_mov_b32 m0, s91
	s_nop 0
	global_load_lds_dwordx4 v[200:201], off
	v_lshl_add_u64 v[200:201], v[212:213], 0, s[46:47]
	s_mov_b32 m0, s88
	s_nop 0
	global_load_lds_dwordx4 v[200:201], off
	s_waitcnt vmcnt(8)
	s_waitcnt lgkmcnt(0)
	s_setprio 0
	s_barrier
	v_mfma_f32_16x16x32_bf16 v[60:63], v[128:131], v[160:163], v[60:63]
	v_mfma_f32_16x16x32_bf16 v[56:59], v[136:139], v[160:163], v[56:59]
	v_mfma_f32_16x16x32_bf16 v[52:55], v[128:131], v[168:171], v[52:55]
	v_mfma_f32_16x16x32_bf16 v[48:51], v[136:139], v[168:171], v[48:51]
	v_mfma_f32_16x16x32_bf16 v[36:39], v[128:131], v[176:179], v[36:39]
	v_mfma_f32_16x16x32_bf16 v[32:35], v[136:139], v[176:179], v[32:35]
	v_mfma_f32_16x16x32_bf16 v[20:23], v[128:131], v[192:195], v[20:23]
	v_mfma_f32_16x16x32_bf16 v[16:19], v[136:139], v[192:195], v[16:19]
	v_mfma_f32_16x16x32_bf16 v[60:63], v[132:135], v[164:167], v[60:63]
	v_mfma_f32_16x16x32_bf16 v[56:59], v[140:143], v[164:167], v[56:59]
	v_mfma_f32_16x16x32_bf16 v[52:55], v[132:135], v[172:175], v[52:55]
	v_mfma_f32_16x16x32_bf16 v[48:51], v[140:143], v[172:175], v[48:51]
	v_mfma_f32_16x16x32_bf16 v[36:39], v[132:135], v[180:183], v[36:39]
	v_mfma_f32_16x16x32_bf16 v[32:35], v[140:143], v[180:183], v[32:35]
	v_mfma_f32_16x16x32_bf16 v[20:23], v[132:135], v[196:199], v[20:23]
	v_mfma_f32_16x16x32_bf16 v[16:19], v[140:143], v[196:199], v[16:19]
	v_mfma_f32_16x16x32_bf16 v[44:47], v[144:147], v[160:163], v[44:47]
	v_mfma_f32_16x16x32_bf16 v[40:43], v[152:155], v[160:163], v[40:43]
	v_mfma_f32_16x16x32_bf16 v[28:31], v[144:147], v[168:171], v[28:31]
	v_mfma_f32_16x16x32_bf16 v[24:27], v[152:155], v[168:171], v[24:27]
	v_mfma_f32_16x16x32_bf16 v[12:15], v[144:147], v[176:179], v[12:15]
	v_mfma_f32_16x16x32_bf16 v[8:11], v[152:155], v[176:179], v[8:11]
	v_mfma_f32_16x16x32_bf16 v[4:7], v[144:147], v[192:195], v[4:7]
	v_mfma_f32_16x16x32_bf16 v[0:3], v[152:155], v[192:195], v[0:3]
	v_mfma_f32_16x16x32_bf16 v[44:47], v[148:151], v[164:167], v[44:47]
	v_mfma_f32_16x16x32_bf16 v[40:43], v[156:159], v[164:167], v[40:43]
	v_mfma_f32_16x16x32_bf16 v[28:31], v[148:151], v[172:175], v[28:31]
	v_mfma_f32_16x16x32_bf16 v[24:27], v[156:159], v[172:175], v[24:27]
	v_mfma_f32_16x16x32_bf16 v[12:15], v[148:151], v[180:183], v[12:15]
	v_mfma_f32_16x16x32_bf16 v[8:11], v[156:159], v[180:183], v[8:11]
	v_mfma_f32_16x16x32_bf16 v[4:7], v[148:151], v[196:199], v[4:7]
	v_mfma_f32_16x16x32_bf16 v[0:3], v[156:159], v[196:199], v[0:3]
	s_barrier
	s_setprio 1
	s_cmp_ge_u32 s44, s11
	s_mov_b32 s6, s44
	s_cbranch_scc1 .LBB0_710

; #define PG8_STAGE(bufoff, gbase, voff) do { _Pragma("unroll") for (int _i = 0; _i < 2; ++_i) \
;         __builtin_amdgcn_global_load_lds((const unsigned*)((const char*)(gbase) + (voff)[_i]), (LAS unsigned*)(lds + (bufoff) + ldsw + _i * 8192), 16, 0, 0); } while (0)
; #define PG8_LDA(dst, b, h) do { _Pragma("unroll") for (int m = 0; m < 4; ++m) _Pragma("unroll") for (int k = 0; k < 2; ++k) dst[m][k] = *(const LAS bf16x8*)(lds + PG8_SA(b, h) + aoff + m * 2048 + k * 1024); } while (0)
; #define PG8_LDB(dst, b, h) do { _Pragma("unroll") for (int n = 0; n < 2; ++n) _Pragma("unroll") for (int k = 0; k < 2; ++k) dst[n][k] = *(const LAS bf16x8*)(lds + PG8_SB(b, h) + boff + n * 2048 + k * 1024); } while (0)
; #define PG8_MMA(ai, bj, At, Bt) do { __builtin_amdgcn_s_setprio(1); _Pragma("unroll") for (int m = 0; m < 4; ++m) _Pragma("unroll") for (int n = 0; n < 2; ++n) _Pragma("unroll") for (int k = 0; k < 2; ++k) \
;         acc[ai][bj][m][n] = __builtin_amdgcn_mfma_f32_16x16x32_bf16(Bt[n][k], At[m][k], acc[ai][bj][m][n], 0, 0, 0); __builtin_amdgcn_s_setprio(0); } while (0)
; #define PG8_WAIT_V(n) asm volatile("s_waitcnt vmcnt(" #n ")" ::: "memory")
; #define PG8_WAIT_L(n) asm volatile("s_waitcnt lgkmcnt(" #n ")" ::: "memory")
; #define PG8_BAR __builtin_amdgcn_s_barrier()
; #define PG8_SCHED __builtin_amdgcn_sched_barrier(0)
; template <class Epi, class Sched>
; DI void gemm_phase(LAS unsigned char* lds, const int K, const Sched& S, const Epi& E, const int wid) {
;     ...
;             const bool last = (t == nt - 2);
;             const char* a1 = cA + (size_t)(t + 1) * kstep;
;             const char* a2 = last ? nA : cA + (size_t)(t + 2) * kstep; const char* b2 = last ? nB : cB + (size_t)(t + 2) * kstep;
;             const char* a3 = a2 + kstep; const char* b3 = b2 + kstep;
;             if (last && has_next) S.a_ready(nxt);
;             PG8_LDB(B0, 0, 0); PG8_LDB(B1, 0, 1); PG8_SCHED; PG8_LDA(At, 0, 0); PG8_STAGE(PG8_SA(1, 1), a1 + hstep, voffA);
;             PG8_WAIT_V(8); PG8_WAIT_L(0); PG8_BAR; PG8_MMA(0, 0, At, B0); PG8_MMA(0, 1, At, B1); PG8_BAR; PG8_SCHED;
;             PG8_LDA(At, 0, 1); PG8_STAGE(PG8_SB(0, 0), b2, voffB); PG8_STAGE(PG8_SB(0, 1), b2 + hstep, voffB); PG8_STAGE(PG8_SA(0, 0), a2, voffA);
;             PG8_WAIT_V(8); PG8_WAIT_L(0); PG8_BAR; PG8_MMA(1, 0, At, B0); PG8_MMA(1, 1, At, B1); PG8_BAR; PG8_SCHED;
.LBB0_814:
	s_or_b32 s8, s54, 1
	s_lshl_b64 s[6:7], s[8:9], 7
	s_add_u32 s55, s50, s6
	s_addc_u32 s58, s51, s7
	s_add_i32 s8, s54, 2
	v_add_u32_e32 v108, s70, v198
	v_add_u32_e32 v124, s73, v198
	s_lshl_b64 s[56:57], s[8:9], 7
	ds_read_b128 v[96:99], v108
	ds_read_b128 v[100:103], v108 offset:1024
	ds_read_b128 v[104:107], v108 offset:2048
	ds_read_b128 v[108:111], v108 offset:3072
	ds_read_b128 v[112:115], v124
	ds_read_b128 v[116:119], v124 offset:1024
	ds_read_b128 v[120:123], v124 offset:2048
	ds_read_b128 v[124:127], v124 offset:3072
	s_add_u32 s59, s50, s56
	s_addc_u32 s60, s51, s57
	s_and_b64 s[6:7], s[4:5], exec
	s_cselect_b32 s7, s60, s35
	s_cselect_b32 s6, s59, s45
	s_add_u32 s56, s48, s56
	s_addc_u32 s57, s49, s57
	s_and_b64 s[4:5], s[4:5], exec
	s_cselect_b32 s5, s57, s31
	s_cselect_b32 s4, s56, s47
	s_add_u32 s56, s55, 0x80000
	s_addc_u32 s57, s58, 0
	s_mov_b32 m0, s89
	v_lshl_add_u64 v[194:195], s[56:57], 0, v[160:161]
	ds_read_b128 v[174:177], v199
	ds_read_b128 v[178:181], v199 offset:1024
	ds_read_b128 v[182:185], v199 offset:2048
	ds_read_b128 v[186:189], v199 offset:3072
	ds_read_b128 v[190:193], v199 offset:4096
	ds_read_b128 v[202:205], v199 offset:5120
	ds_read_b128 v[208:211], v199 offset:6144
	ds_read_b128 v[212:215], v199 offset:7168
	global_load_lds_dwordx4 v[194:195], off
	v_lshl_add_u64 v[194:195], s[56:57], 0, v[164:165]
	s_mov_b32 m0, s26
	s_nop 0
	global_load_lds_dwordx4 v[194:195], off
	s_waitcnt vmcnt(8)
	s_waitcnt lgkmcnt(0)
	s_setprio 0
	s_barrier
	v_mfma_f32_16x16x32_bf16 v[156:159], v[96:99], v[174:177], v[156:159]
	v_mfma_f32_16x16x32_bf16 v[60:63], v[104:107], v[174:177], v[60:63]
	v_mfma_f32_16x16x32_bf16 v[148:151], v[96:99], v[182:185], v[148:151]
	v_mfma_f32_16x16x32_bf16 v[52:55], v[104:107], v[182:185], v[52:55]
	v_mfma_f32_16x16x32_bf16 v[144:147], v[96:99], v[190:193], v[144:147]
	v_mfma_f32_16x16x32_bf16 v[48:51], v[104:107], v[190:193], v[48:51]
	v_mfma_f32_16x16x32_bf16 v[152:155], v[96:99], v[208:211], v[152:155]
	v_mfma_f32_16x16x32_bf16 v[56:59], v[104:107], v[208:211], v[56:59]
	v_mfma_f32_16x16x32_bf16 v[156:159], v[100:103], v[178:181], v[156:159]
	v_mfma_f32_16x16x32_bf16 v[60:63], v[108:111], v[178:181], v[60:63]
	v_mfma_f32_16x16x32_bf16 v[148:151], v[100:103], v[186:189], v[148:151]
	v_mfma_f32_16x16x32_bf16 v[52:55], v[108:111], v[186:189], v[52:55]
	v_mfma_f32_16x16x32_bf16 v[144:147], v[100:103], v[202:205], v[144:147]
	v_mfma_f32_16x16x32_bf16 v[48:51], v[108:111], v[202:205], v[48:51]
	v_mfma_f32_16x16x32_bf16 v[152:155], v[100:103], v[212:215], v[152:155]
	v_mfma_f32_16x16x32_bf16 v[56:59], v[108:111], v[212:215], v[56:59]
	v_mfma_f32_16x16x32_bf16 v[140:143], v[112:115], v[174:177], v[140:143]
	v_mfma_f32_16x16x32_bf16 v[44:47], v[120:123], v[174:177], v[44:47]
	v_mfma_f32_16x16x32_bf16 v[132:135], v[112:115], v[182:185], v[132:135]
	v_mfma_f32_16x16x32_bf16 v[36:39], v[120:123], v[182:185], v[36:39]
	v_mfma_f32_16x16x32_bf16 v[128:131], v[112:115], v[190:193], v[128:131]
	v_mfma_f32_16x16x32_bf16 v[32:35], v[120:123], v[190:193], v[32:35]
	v_mfma_f32_16x16x32_bf16 v[136:139], v[112:115], v[208:211], v[136:139]
	v_mfma_f32_16x16x32_bf16 v[40:43], v[120:123], v[208:211], v[40:43]
	v_mfma_f32_16x16x32_bf16 v[140:143], v[116:119], v[178:181], v[140:143]
	v_mfma_f32_16x16x32_bf16 v[44:47], v[124:127], v[178:181], v[44:47]
	v_mfma_f32_16x16x32_bf16 v[132:135], v[116:119], v[186:189], v[132:135]
	v_mfma_f32_16x16x32_bf16 v[36:39], v[124:127], v[186:189], v[36:39]
	v_mfma_f32_16x16x32_bf16 v[128:131], v[116:119], v[202:205], v[128:131]
	v_mfma_f32_16x16x32_bf16 v[32:35], v[124:127], v[202:205], v[32:35]
	v_mfma_f32_16x16x32_bf16 v[136:139], v[116:119], v[212:215], v[136:139]
	v_mfma_f32_16x16x32_bf16 v[40:43], v[124:127], v[212:215], v[40:43]
	s_barrier
	s_setprio 1
	s_mov_b32 m0, s27
	v_lshl_add_u64 v[194:195], s[4:5], 0, v[162:163]
	s_add_u32 s56, s4, 0x80000
	ds_read_b128 v[174:177], v199 offset:16384
	ds_read_b128 v[178:181], v199 offset:17408
	ds_read_b128 v[182:185], v199 offset:18432
	ds_read_b128 v[186:189], v199 offset:19456
	ds_read_b128 v[190:193], v199 offset:20480
	ds_read_b128 v[202:205], v199 offset:21504
	ds_read_b128 v[208:211], v199 offset:22528
	ds_read_b128 v[212:215], v199 offset:23552
	global_load_lds_dwordx4 v[194:195], off
	v_lshl_add_u64 v[216:217], s[4:5], 0, v[166:167]
	s_mov_b32 m0, s22
	s_addc_u32 s57, s5, 0
	global_load_lds_dwordx4 v[216:217], off
	v_lshl_add_u64 v[218:219], s[56:57], 0, v[162:163]
	s_mov_b32 m0, s23
	v_lshl_add_u64 v[220:221], s[6:7], 0, v[164:165]
	global_load_lds_dwordx4 v[218:219], off
	v_lshl_add_u64 v[218:219], s[56:57], 0, v[166:167]
	s_mov_b32 m0, s87
	s_nop 0
	global_load_lds_dwordx4 v[218:219], off
	v_lshl_add_u64 v[218:219], s[6:7], 0, v[160:161]
	s_mov_b32 m0, s85
	s_nop 0
	global_load_lds_dwordx4 v[218:219], off
	s_mov_b32 m0, s33
	s_nop 0
	global_load_lds_dwordx4 v[220:221], off
	s_waitcnt vmcnt(8)
	s_waitcnt lgkmcnt(0)
	s_setprio 0
	s_barrier
; #define PG8_STAGE(bufoff, gbase, voff) do { _Pragma("unroll") for (int _i = 0; _i < 2; ++_i) \
;         __builtin_amdgcn_global_load_lds((const unsigned*)((const char*)(gbase) + (voff)[_i]), (LAS unsigned*)(lds + (bufoff) + ldsw + _i * 8192), 16, 0, 0); } while (0)
; #define PG8_LDA(dst, b, h) do { _Pragma("unroll") for (int m = 0; m < 4; ++m) _Pragma("unroll") for (int k = 0; k < 2; ++k) dst[m][k] = *(const LAS bf16x8*)(lds + PG8_SA(b, h) + aoff + m * 2048 + k * 1024); } while (0)
; #define PG8_LDB(dst, b, h) do { _Pragma("unroll") for (int n = 0; n < 2; ++n) _Pragma("unroll") for (int k = 0; k < 2; ++k) dst[n][k] = *(const LAS bf16x8*)(lds + PG8_SB(b, h) + boff + n * 2048 + k * 1024); } while (0)
; #define PG8_MMA(ai, bj, At, Bt) do { __builtin_amdgcn_s_setprio(1); _Pragma("unroll") for (int m = 0; m < 4; ++m) _Pragma("unroll") for (int n = 0; n < 2; ++n) _Pragma("unroll") for (int k = 0; k < 2; ++k) \
;         acc[ai][bj][m][n] = __builtin_amdgcn_mfma_f32_16x16x32_bf16(Bt[n][k], At[m][k], acc[ai][bj][m][n], 0, 0, 0); __builtin_amdgcn_s_setprio(0); } while (0)
; #define PG8_WAIT_V(n) asm volatile("s_waitcnt vmcnt(" #n ")" ::: "memory")
; #define PG8_WAIT_L(n) asm volatile("s_waitcnt lgkmcnt(" #n ")" ::: "memory")
; #define PG8_BAR __builtin_amdgcn_s_barrier()
; #define PG8_SCHED __builtin_amdgcn_sched_barrier(0)
; template <class Epi, class Sched>
; DI void gemm_phase(LAS unsigned char* lds, const int K, const Sched& S, const Epi& E, const int wid) {
;     ...
;             PG8_WAIT_V(8); PG8_WAIT_L(0); PG8_BAR; PG8_MMA(1, 0, At, B0); PG8_MMA(1, 1, At, B1); PG8_BAR; PG8_SCHED;
;             PG8_LDB(B0, 1, 0); PG8_LDB(B1, 1, 1); PG8_SCHED; PG8_LDA(At, 1, 0); PG8_STAGE(PG8_SA(0, 1), a2 + hstep, voffA);
;             PG8_WAIT_V(8); PG8_WAIT_L(0); PG8_BAR; PG8_MMA(0, 0, At, B0); PG8_MMA(0, 1, At, B1); PG8_BAR; PG8_SCHED;
	v_mfma_f32_16x16x32_bf16 v[92:95], v[96:99], v[174:177], v[92:95]
	v_mfma_f32_16x16x32_bf16 v[28:31], v[104:107], v[174:177], v[28:31]
	v_mfma_f32_16x16x32_bf16 v[84:87], v[96:99], v[182:185], v[84:87]
	v_mfma_f32_16x16x32_bf16 v[20:23], v[104:107], v[182:185], v[20:23]
	v_mfma_f32_16x16x32_bf16 v[80:83], v[96:99], v[190:193], v[80:83]
	v_mfma_f32_16x16x32_bf16 v[16:19], v[104:107], v[190:193], v[16:19]
	v_mfma_f32_16x16x32_bf16 v[88:91], v[96:99], v[208:211], v[88:91]
	v_mfma_f32_16x16x32_bf16 v[24:27], v[104:107], v[208:211], v[24:27]
	v_mfma_f32_16x16x32_bf16 v[92:95], v[100:103], v[178:181], v[92:95]
	v_mfma_f32_16x16x32_bf16 v[28:31], v[108:111], v[178:181], v[28:31]
	v_mfma_f32_16x16x32_bf16 v[84:87], v[100:103], v[186:189], v[84:87]
	v_mfma_f32_16x16x32_bf16 v[20:23], v[108:111], v[186:189], v[20:23]
	v_mfma_f32_16x16x32_bf16 v[80:83], v[100:103], v[202:205], v[80:83]
	v_mfma_f32_16x16x32_bf16 v[16:19], v[108:111], v[202:205], v[16:19]
	v_mfma_f32_16x16x32_bf16 v[88:91], v[100:103], v[212:215], v[88:91]
	v_mfma_f32_16x16x32_bf16 v[24:27], v[108:111], v[212:215], v[24:27]
	v_mfma_f32_16x16x32_bf16 v[76:79], v[112:115], v[174:177], v[76:79]
	v_mfma_f32_16x16x32_bf16 v[12:15], v[120:123], v[174:177], v[12:15]
	v_mfma_f32_16x16x32_bf16 v[68:71], v[112:115], v[182:185], v[68:71]
	v_mfma_f32_16x16x32_bf16 v[4:7], v[120:123], v[182:185], v[4:7]
	v_mfma_f32_16x16x32_bf16 v[64:67], v[112:115], v[190:193], v[64:67]
	v_mfma_f32_16x16x32_bf16 v[0:3], v[120:123], v[190:193], v[0:3]
	v_mfma_f32_16x16x32_bf16 v[72:75], v[112:115], v[208:211], v[72:75]
	v_mfma_f32_16x16x32_bf16 v[8:11], v[120:123], v[208:211], v[8:11]
	v_mfma_f32_16x16x32_bf16 v[76:79], v[116:119], v[178:181], v[76:79]
	v_mfma_f32_16x16x32_bf16 v[12:15], v[124:127], v[178:181], v[12:15]
	v_mfma_f32_16x16x32_bf16 v[68:71], v[116:119], v[186:189], v[68:71]
	v_mfma_f32_16x16x32_bf16 v[4:7], v[124:127], v[186:189], v[4:7]
	v_mfma_f32_16x16x32_bf16 v[64:67], v[116:119], v[202:205], v[64:67]
	v_mfma_f32_16x16x32_bf16 v[0:3], v[124:127], v[202:205], v[0:3]
	v_mfma_f32_16x16x32_bf16 v[72:75], v[116:119], v[212:215], v[72:75]
	v_mfma_f32_16x16x32_bf16 v[8:11], v[124:127], v[212:215], v[8:11]
	s_barrier
	s_setprio 1
	v_add_u32_e32 v108, s96, v198
	v_add_u32_e32 v124, s90, v198
	ds_read_b128 v[96:99], v108
	ds_read_b128 v[100:103], v108 offset:1024
	ds_read_b128 v[104:107], v108 offset:2048
	ds_read_b128 v[108:111], v108 offset:3072
	ds_read_b128 v[112:115], v124
	ds_read_b128 v[116:119], v124 offset:1024
	ds_read_b128 v[120:123], v124 offset:2048
	ds_read_b128 v[124:127], v124 offset:3072
	s_add_u32 s6, s6, 0x80000
	s_addc_u32 s7, s7, 0
	s_mov_b32 m0, s29
	v_lshl_add_u64 v[222:223], s[6:7], 0, v[160:161]
	ds_read_b128 v[174:177], v199 offset:32768
	ds_read_b128 v[178:181], v199 offset:33792
	ds_read_b128 v[182:185], v199 offset:34816
	ds_read_b128 v[186:189], v199 offset:35840
	ds_read_b128 v[190:193], v199 offset:36864
	ds_read_b128 v[202:205], v199 offset:37888
	ds_read_b128 v[208:211], v199 offset:38912
	ds_read_b128 v[212:215], v199 offset:39936
	global_load_lds_dwordx4 v[222:223], off
	v_lshl_add_u64 v[222:223], s[6:7], 0, v[164:165]
	s_mov_b32 m0, s97
	s_nop 0
	global_load_lds_dwordx4 v[222:223], off
	s_waitcnt vmcnt(8)
	s_waitcnt lgkmcnt(0)
	s_setprio 0
	s_barrier
	v_mfma_f32_16x16x32_bf16 v[156:159], v[96:99], v[174:177], v[156:159]
	v_mfma_f32_16x16x32_bf16 v[60:63], v[104:107], v[174:177], v[60:63]
	v_mfma_f32_16x16x32_bf16 v[148:151], v[96:99], v[182:185], v[148:151]
	v_mfma_f32_16x16x32_bf16 v[52:55], v[104:107], v[182:185], v[52:55]
	v_mfma_f32_16x16x32_bf16 v[144:147], v[96:99], v[190:193], v[144:147]
	v_mfma_f32_16x16x32_bf16 v[48:51], v[104:107], v[190:193], v[48:51]
	v_mfma_f32_16x16x32_bf16 v[152:155], v[96:99], v[208:211], v[152:155]
	v_mfma_f32_16x16x32_bf16 v[56:59], v[104:107], v[208:211], v[56:59]
	v_mfma_f32_16x16x32_bf16 v[156:159], v[100:103], v[178:181], v[156:159]
	v_mfma_f32_16x16x32_bf16 v[60:63], v[108:111], v[178:181], v[60:63]
	v_mfma_f32_16x16x32_bf16 v[148:151], v[100:103], v[186:189], v[148:151]
	v_mfma_f32_16x16x32_bf16 v[52:55], v[108:111], v[186:189], v[52:55]
	v_mfma_f32_16x16x32_bf16 v[144:147], v[100:103], v[202:205], v[144:147]
	v_mfma_f32_16x16x32_bf16 v[48:51], v[108:111], v[202:205], v[48:51]
	v_mfma_f32_16x16x32_bf16 v[152:155], v[100:103], v[212:215], v[152:155]
	v_mfma_f32_16x16x32_bf16 v[56:59], v[108:111], v[212:215], v[56:59]
	v_mfma_f32_16x16x32_bf16 v[140:143], v[112:115], v[174:177], v[140:143]
	v_mfma_f32_16x16x32_bf16 v[44:47], v[120:123], v[174:177], v[44:47]
	v_mfma_f32_16x16x32_bf16 v[132:135], v[112:115], v[182:185], v[132:135]
	v_mfma_f32_16x16x32_bf16 v[36:39], v[120:123], v[182:185], v[36:39]
	v_mfma_f32_16x16x32_bf16 v[128:131], v[112:115], v[190:193], v[128:131]
	v_mfma_f32_16x16x32_bf16 v[32:35], v[120:123], v[190:193], v[32:35]
	v_mfma_f32_16x16x32_bf16 v[136:139], v[112:115], v[208:211], v[136:139]
	v_mfma_f32_16x16x32_bf16 v[40:43], v[120:123], v[208:211], v[40:43]
	v_mfma_f32_16x16x32_bf16 v[140:143], v[116:119], v[178:181], v[140:143]
	v_mfma_f32_16x16x32_bf16 v[44:47], v[124:127], v[178:181], v[44:47]
	v_mfma_f32_16x16x32_bf16 v[132:135], v[116:119], v[186:189], v[132:135]
	v_mfma_f32_16x16x32_bf16 v[36:39], v[124:127], v[186:189], v[36:39]
	v_mfma_f32_16x16x32_bf16 v[128:131], v[116:119], v[202:205], v[128:131]
	v_mfma_f32_16x16x32_bf16 v[32:35], v[124:127], v[202:205], v[32:35]
	v_mfma_f32_16x16x32_bf16 v[136:139], v[116:119], v[212:215], v[136:139]
	v_mfma_f32_16x16x32_bf16 v[40:43], v[124:127], v[212:215], v[40:43]
	s_barrier
; #define PG8_STAGE(bufoff, gbase, voff) do { _Pragma("unroll") for (int _i = 0; _i < 2; ++_i) \
;         __builtin_amdgcn_global_load_lds((const unsigned*)((const char*)(gbase) + (voff)[_i]), (LAS unsigned*)(lds + (bufoff) + ldsw + _i * 8192), 16, 0, 0); } while (0)
; #define PG8_LDA(dst, b, h) do { _Pragma("unroll") for (int m = 0; m < 4; ++m) _Pragma("unroll") for (int k = 0; k < 2; ++k) dst[m][k] = *(const LAS bf16x8*)(lds + PG8_SA(b, h) + aoff + m * 2048 + k * 1024); } while (0)
; #define PG8_MMA(ai, bj, At, Bt) do { __builtin_amdgcn_s_setprio(1); _Pragma("unroll") for (int m = 0; m < 4; ++m) _Pragma("unroll") for (int n = 0; n < 2; ++n) _Pragma("unroll") for (int k = 0; k < 2; ++k) \
;         acc[ai][bj][m][n] = __builtin_amdgcn_mfma_f32_16x16x32_bf16(Bt[n][k], At[m][k], acc[ai][bj][m][n], 0, 0, 0); __builtin_amdgcn_s_setprio(0); } while (0)
; #define PG8_WAIT_V(n) asm volatile("s_waitcnt vmcnt(" #n ")" ::: "memory")
; #define PG8_WAIT_L(n) asm volatile("s_waitcnt lgkmcnt(" #n ")" ::: "memory")
; #define PG8_BAR __builtin_amdgcn_s_barrier()
; #define PG8_SCHED __builtin_amdgcn_sched_barrier(0)
; template <class Epi, class Sched>
; DI void gemm_phase(LAS unsigned char* lds, const int K, const Sched& S, const Epi& E, const int wid) {
;     ...
;             PG8_LDA(At, 1, 1); PG8_STAGE(PG8_SB(1, 0), b3, voffB); PG8_STAGE(PG8_SB(1, 1), b3 + hstep, voffB); PG8_STAGE(PG8_SA(1, 0), a3, voffA);
;             PG8_WAIT_V(8); PG8_WAIT_L(0); PG8_BAR; PG8_MMA(1, 0, At, B0); PG8_MMA(1, 1, At, B1); PG8_BAR; PG8_SCHED;
;         }
	s_setprio 1
	s_mov_b32 m0, s94
	v_lshl_add_u64 v[194:195], v[194:195], 0, s[18:19]
	s_add_u32 s4, s4, 0x80080
	ds_read_b128 v[174:177], v199 offset:49152
	ds_read_b128 v[178:181], v199 offset:50176
	ds_read_b128 v[182:185], v199 offset:51200
	ds_read_b128 v[186:189], v199 offset:52224
	ds_read_b128 v[190:193], v199 offset:53248
	ds_read_b128 v[202:205], v199 offset:54272
	ds_read_b128 v[208:211], v199 offset:55296
	ds_read_b128 v[212:215], v199 offset:56320
	global_load_lds_dwordx4 v[194:195], off
	v_lshl_add_u64 v[194:195], v[216:217], 0, s[18:19]
	s_mov_b32 m0, s84
	s_addc_u32 s5, s5, 0
	global_load_lds_dwordx4 v[194:195], off
	v_lshl_add_u64 v[194:195], s[4:5], 0, v[162:163]
	s_mov_b32 m0, s86
	s_nop 0
	global_load_lds_dwordx4 v[194:195], off
	v_lshl_add_u64 v[194:195], s[4:5], 0, v[166:167]
	s_mov_b32 m0, s28
	s_nop 0
	global_load_lds_dwordx4 v[194:195], off
	v_lshl_add_u64 v[194:195], v[218:219], 0, s[18:19]
	s_mov_b32 m0, s91
	s_nop 0
	global_load_lds_dwordx4 v[194:195], off
	v_lshl_add_u64 v[194:195], v[220:221], 0, s[18:19]
	s_mov_b32 m0, s88
	s_nop 0
	global_load_lds_dwordx4 v[194:195], off
	s_waitcnt vmcnt(8)
	s_waitcnt lgkmcnt(0)
	s_setprio 0
	s_barrier
	v_mfma_f32_16x16x32_bf16 v[92:95], v[96:99], v[174:177], v[92:95]
	v_mfma_f32_16x16x32_bf16 v[28:31], v[104:107], v[174:177], v[28:31]
	v_mfma_f32_16x16x32_bf16 v[84:87], v[96:99], v[182:185], v[84:87]
	v_mfma_f32_16x16x32_bf16 v[20:23], v[104:107], v[182:185], v[20:23]
	v_mfma_f32_16x16x32_bf16 v[80:83], v[96:99], v[190:193], v[80:83]
	v_mfma_f32_16x16x32_bf16 v[16:19], v[104:107], v[190:193], v[16:19]
	v_mfma_f32_16x16x32_bf16 v[88:91], v[96:99], v[208:211], v[88:91]
	v_mfma_f32_16x16x32_bf16 v[24:27], v[104:107], v[208:211], v[24:27]
	v_mfma_f32_16x16x32_bf16 v[92:95], v[100:103], v[178:181], v[92:95]
	v_mfma_f32_16x16x32_bf16 v[28:31], v[108:111], v[178:181], v[28:31]
	v_mfma_f32_16x16x32_bf16 v[84:87], v[100:103], v[186:189], v[84:87]
	v_mfma_f32_16x16x32_bf16 v[20:23], v[108:111], v[186:189], v[20:23]
	v_mfma_f32_16x16x32_bf16 v[80:83], v[100:103], v[202:205], v[80:83]
	v_mfma_f32_16x16x32_bf16 v[16:19], v[108:111], v[202:205], v[16:19]
	v_mfma_f32_16x16x32_bf16 v[88:91], v[100:103], v[212:215], v[88:91]
	v_mfma_f32_16x16x32_bf16 v[24:27], v[108:111], v[212:215], v[24:27]
	v_mfma_f32_16x16x32_bf16 v[76:79], v[112:115], v[174:177], v[76:79]
	v_mfma_f32_16x16x32_bf16 v[12:15], v[120:123], v[174:177], v[12:15]
	v_mfma_f32_16x16x32_bf16 v[68:71], v[112:115], v[182:185], v[68:71]
	v_mfma_f32_16x16x32_bf16 v[4:7], v[120:123], v[182:185], v[4:7]
	v_mfma_f32_16x16x32_bf16 v[64:67], v[112:115], v[190:193], v[64:67]
	v_mfma_f32_16x16x32_bf16 v[0:3], v[120:123], v[190:193], v[0:3]
	v_mfma_f32_16x16x32_bf16 v[72:75], v[112:115], v[208:211], v[72:75]
	v_mfma_f32_16x16x32_bf16 v[8:11], v[120:123], v[208:211], v[8:11]
	v_mfma_f32_16x16x32_bf16 v[76:79], v[116:119], v[178:181], v[76:79]
	v_mfma_f32_16x16x32_bf16 v[12:15], v[124:127], v[178:181], v[12:15]
	v_mfma_f32_16x16x32_bf16 v[68:71], v[116:119], v[186:189], v[68:71]
	v_mfma_f32_16x16x32_bf16 v[4:7], v[124:127], v[186:189], v[4:7]
	v_mfma_f32_16x16x32_bf16 v[64:67], v[116:119], v[202:205], v[64:67]
	v_mfma_f32_16x16x32_bf16 v[0:3], v[124:127], v[202:205], v[0:3]
	v_mfma_f32_16x16x32_bf16 v[72:75], v[116:119], v[212:215], v[72:75]
	v_mfma_f32_16x16x32_bf16 v[8:11], v[124:127], v[212:215], v[8:11]
	s_barrier
	s_setprio 1
	s_cmp_gt_u32 s54, 29
	s_mov_b32 s54, s8
	s_cbranch_scc1 .LBB0_818

; #define PG8_STAGE(bufoff, gbase, voff) do { _Pragma("unroll") for (int _i = 0; _i < 2; ++_i) \
;         __builtin_amdgcn_global_load_lds((const unsigned*)((const char*)(gbase) + (voff)[_i]), (LAS unsigned*)(lds + (bufoff) + ldsw + _i * 8192), 16, 0, 0); } while (0)
; #define PG8_LDA(dst, b, h) do { _Pragma("unroll") for (int m = 0; m < 4; ++m) _Pragma("unroll") for (int k = 0; k < 2; ++k) dst[m][k] = *(const LAS bf16x8*)(lds + PG8_SA(b, h) + aoff + m * 2048 + k * 1024); } while (0)
; #define PG8_LDB(dst, b, h) do { _Pragma("unroll") for (int n = 0; n < 2; ++n) _Pragma("unroll") for (int k = 0; k < 2; ++k) dst[n][k] = *(const LAS bf16x8*)(lds + PG8_SB(b, h) + boff + n * 2048 + k * 1024); } while (0)
; #define PG8_MMA(ai, bj, At, Bt) do { __builtin_amdgcn_s_setprio(1); _Pragma("unroll") for (int m = 0; m < 4; ++m) _Pragma("unroll") for (int n = 0; n < 2; ++n) _Pragma("unroll") for (int k = 0; k < 2; ++k) \
;         acc[ai][bj][m][n] = __builtin_amdgcn_mfma_f32_16x16x32_bf16(Bt[n][k], At[m][k], acc[ai][bj][m][n], 0, 0, 0); __builtin_amdgcn_s_setprio(0); } while (0)
; #define PG8_WAIT_V(n) asm volatile("s_waitcnt vmcnt(" #n ")" ::: "memory")
; #define PG8_WAIT_L(n) asm volatile("s_waitcnt lgkmcnt(" #n ")" ::: "memory")
; #define PG8_BAR __builtin_amdgcn_s_barrier()
; #define PG8_SCHED __builtin_amdgcn_sched_barrier(0)
; template <class Epi, class Sched>
; DI void gemm_phase(LAS unsigned char* lds, const int K, const Sched& S, const Epi& E, const int wid) {
;     ...
;             const bool last = (t == nt - 2);
;             const char* a1 = cA + (size_t)(t + 1) * kstep;
;             const char* a2 = last ? nA : cA + (size_t)(t + 2) * kstep; const char* b2 = last ? nB : cB + (size_t)(t + 2) * kstep;
;             const char* a3 = a2 + kstep; const char* b3 = b2 + kstep;
;             if (last && has_next) S.a_ready(nxt);
;             PG8_LDB(B0, 0, 0); PG8_LDB(B1, 0, 1); PG8_SCHED; PG8_LDA(At, 0, 0); PG8_STAGE(PG8_SA(1, 1), a1 + hstep, voffA);
;             PG8_WAIT_V(8); PG8_WAIT_L(0); PG8_BAR; PG8_MMA(0, 0, At, B0); PG8_MMA(0, 1, At, B1); PG8_BAR; PG8_SCHED;
;             PG8_LDA(At, 0, 1); PG8_STAGE(PG8_SB(0, 0), b2, voffB); PG8_STAGE(PG8_SB(0, 1), b2 + hstep, voffB); PG8_STAGE(PG8_SA(0, 0), a2, voffA);
;             PG8_WAIT_V(8); PG8_WAIT_L(0); PG8_BAR; PG8_MMA(1, 0, At, B0); PG8_MMA(1, 1, At, B1); PG8_BAR; PG8_SCHED;
.LBB0_1068:
	ds_read_b128 v[128:131], v179
	ds_read_b128 v[132:135], v179 offset:1024
	ds_read_b128 v[136:139], v179 offset:2048
	ds_read_b128 v[140:143], v179 offset:3072
	ds_read_b128 v[144:147], v180
	ds_read_b128 v[160:163], v180 offset:1024
	ds_read_b128 v[164:167], v180 offset:2048
	ds_read_b128 v[168:171], v180 offset:3072
	s_add_i32 s38, s6, 2
	s_add_u32 s4, s18, 0x100
	s_addc_u32 s5, s19, 0
	s_cmp_eq_u32 s35, s6
	s_cselect_b32 s6, s16, s36
	s_cselect_b32 s21, s15, s5
	s_cselect_b32 s20, s14, s4
	s_cselect_b32 s7, s17, s37
	s_mov_b32 m0, s89
	v_lshl_add_u64 v[212:213], s[18:19], 0, v[156:157]
	ds_read_b128 v[172:175], v181
	ds_read_b128 v[182:185], v181 offset:1024
	ds_read_b128 v[186:189], v181 offset:2048
	ds_read_b128 v[190:193], v181 offset:3072
	ds_read_b128 v[194:197], v181 offset:4096
	ds_read_b128 v[198:201], v181 offset:5120
	ds_read_b128 v[202:205], v181 offset:6144
	ds_read_b128 v[208:211], v181 offset:7168
	global_load_lds_dwordx4 v[212:213], off
	v_lshl_add_u64 v[212:213], s[18:19], 0, v[158:159]
	s_mov_b32 m0, s26
	s_nop 0
	global_load_lds_dwordx4 v[212:213], off
	s_waitcnt vmcnt(8)
	s_waitcnt lgkmcnt(0)
	s_setprio 0
	s_barrier
	v_mfma_f32_16x16x32_bf16 v[124:127], v[128:131], v[172:175], v[124:127]
	v_mfma_f32_16x16x32_bf16 v[120:123], v[136:139], v[172:175], v[120:123]
	v_mfma_f32_16x16x32_bf16 v[116:119], v[128:131], v[186:189], v[116:119]
	v_mfma_f32_16x16x32_bf16 v[112:115], v[136:139], v[186:189], v[112:115]
	v_mfma_f32_16x16x32_bf16 v[100:103], v[128:131], v[194:197], v[100:103]
	v_mfma_f32_16x16x32_bf16 v[96:99], v[136:139], v[194:197], v[96:99]
	v_mfma_f32_16x16x32_bf16 v[84:87], v[128:131], v[202:205], v[84:87]
	v_mfma_f32_16x16x32_bf16 v[80:83], v[136:139], v[202:205], v[80:83]
	v_mfma_f32_16x16x32_bf16 v[124:127], v[132:135], v[182:185], v[124:127]
	v_mfma_f32_16x16x32_bf16 v[120:123], v[140:143], v[182:185], v[120:123]
	v_mfma_f32_16x16x32_bf16 v[116:119], v[132:135], v[190:193], v[116:119]
	v_mfma_f32_16x16x32_bf16 v[112:115], v[140:143], v[190:193], v[112:115]
	v_mfma_f32_16x16x32_bf16 v[100:103], v[132:135], v[198:201], v[100:103]
	v_mfma_f32_16x16x32_bf16 v[96:99], v[140:143], v[198:201], v[96:99]
	v_mfma_f32_16x16x32_bf16 v[84:87], v[132:135], v[208:211], v[84:87]
	v_mfma_f32_16x16x32_bf16 v[80:83], v[140:143], v[208:211], v[80:83]
	v_mfma_f32_16x16x32_bf16 v[108:111], v[144:147], v[172:175], v[108:111]
	v_mfma_f32_16x16x32_bf16 v[104:107], v[164:167], v[172:175], v[104:107]
	v_mfma_f32_16x16x32_bf16 v[92:95], v[144:147], v[186:189], v[92:95]
	v_mfma_f32_16x16x32_bf16 v[88:91], v[164:167], v[186:189], v[88:91]
	v_mfma_f32_16x16x32_bf16 v[76:79], v[144:147], v[194:197], v[76:79]
	v_mfma_f32_16x16x32_bf16 v[72:75], v[164:167], v[194:197], v[72:75]
	v_mfma_f32_16x16x32_bf16 v[68:71], v[144:147], v[202:205], v[68:71]
	v_mfma_f32_16x16x32_bf16 v[64:67], v[164:167], v[202:205], v[64:67]
	v_mfma_f32_16x16x32_bf16 v[108:111], v[160:163], v[182:185], v[108:111]
	v_mfma_f32_16x16x32_bf16 v[104:107], v[168:171], v[182:185], v[104:107]
	v_mfma_f32_16x16x32_bf16 v[92:95], v[160:163], v[190:193], v[92:95]
	v_mfma_f32_16x16x32_bf16 v[88:91], v[168:171], v[190:193], v[88:91]
	v_mfma_f32_16x16x32_bf16 v[76:79], v[160:163], v[198:201], v[76:79]
	v_mfma_f32_16x16x32_bf16 v[72:75], v[168:171], v[198:201], v[72:75]
	v_mfma_f32_16x16x32_bf16 v[68:71], v[160:163], v[208:211], v[68:71]
	v_mfma_f32_16x16x32_bf16 v[64:67], v[168:171], v[208:211], v[64:67]
	s_barrier
	s_setprio 1
	s_mov_b32 m0, s27
	v_lshl_add_u64 v[212:213], s[6:7], 0, v[150:151]
	s_add_u32 s18, s6, 0x164000
	ds_read_b128 v[172:175], v181 offset:16384
	ds_read_b128 v[182:185], v181 offset:17408
	ds_read_b128 v[186:189], v181 offset:18432
	ds_read_b128 v[190:193], v181 offset:19456
	ds_read_b128 v[194:197], v181 offset:20480
	ds_read_b128 v[198:201], v181 offset:21504
	ds_read_b128 v[202:205], v181 offset:22528
	ds_read_b128 v[208:211], v181 offset:23552
	global_load_lds_dwordx4 v[212:213], off
	v_lshl_add_u64 v[214:215], s[6:7], 0, v[154:155]
	s_mov_b32 m0, s22
	s_addc_u32 s19, s7, 0
	global_load_lds_dwordx4 v[214:215], off
	v_lshl_add_u64 v[216:217], s[18:19], 0, v[150:151]
	s_mov_b32 m0, s23
	v_lshl_add_u64 v[218:219], s[20:21], 0, v[152:153]
	global_load_lds_dwordx4 v[216:217], off
	v_lshl_add_u64 v[216:217], s[18:19], 0, v[154:155]
	s_mov_b32 m0, s87
	s_nop 0
	global_load_lds_dwordx4 v[216:217], off
	v_lshl_add_u64 v[216:217], s[20:21], 0, v[148:149]
	s_mov_b32 m0, s85
	s_nop 0
	global_load_lds_dwordx4 v[216:217], off
	s_mov_b32 m0, s33
	s_nop 0
	global_load_lds_dwordx4 v[218:219], off
	s_waitcnt vmcnt(8)
	s_waitcnt lgkmcnt(0)
	s_setprio 0
	s_barrier
; #define PG8_STAGE(bufoff, gbase, voff) do { _Pragma("unroll") for (int _i = 0; _i < 2; ++_i) \
;         __builtin_amdgcn_global_load_lds((const unsigned*)((const char*)(gbase) + (voff)[_i]), (LAS unsigned*)(lds + (bufoff) + ldsw + _i * 8192), 16, 0, 0); } while (0)
; #define PG8_LDA(dst, b, h) do { _Pragma("unroll") for (int m = 0; m < 4; ++m) _Pragma("unroll") for (int k = 0; k < 2; ++k) dst[m][k] = *(const LAS bf16x8*)(lds + PG8_SA(b, h) + aoff + m * 2048 + k * 1024); } while (0)
; #define PG8_LDB(dst, b, h) do { _Pragma("unroll") for (int n = 0; n < 2; ++n) _Pragma("unroll") for (int k = 0; k < 2; ++k) dst[n][k] = *(const LAS bf16x8*)(lds + PG8_SB(b, h) + boff + n * 2048 + k * 1024); } while (0)
; #define PG8_MMA(ai, bj, At, Bt) do { __builtin_amdgcn_s_setprio(1); _Pragma("unroll") for (int m = 0; m < 4; ++m) _Pragma("unroll") for (int n = 0; n < 2; ++n) _Pragma("unroll") for (int k = 0; k < 2; ++k) \
;         acc[ai][bj][m][n] = __builtin_amdgcn_mfma_f32_16x16x32_bf16(Bt[n][k], At[m][k], acc[ai][bj][m][n], 0, 0, 0); __builtin_amdgcn_s_setprio(0); } while (0)
; #define PG8_WAIT_V(n) asm volatile("s_waitcnt vmcnt(" #n ")" ::: "memory")
; #define PG8_WAIT_L(n) asm volatile("s_waitcnt lgkmcnt(" #n ")" ::: "memory")
; #define PG8_BAR __builtin_amdgcn_s_barrier()
; #define PG8_SCHED __builtin_amdgcn_sched_barrier(0)
; template <class Epi, class Sched>
; DI void gemm_phase(LAS unsigned char* lds, const int K, const Sched& S, const Epi& E, const int wid) {
;     ...
;             PG8_WAIT_V(8); PG8_WAIT_L(0); PG8_BAR; PG8_MMA(1, 0, At, B0); PG8_MMA(1, 1, At, B1); PG8_BAR; PG8_SCHED;
;             PG8_LDB(B0, 1, 0); PG8_LDB(B1, 1, 1); PG8_SCHED; PG8_LDA(At, 1, 0); PG8_STAGE(PG8_SA(0, 1), a2 + hstep, voffA);
;             PG8_WAIT_V(8); PG8_WAIT_L(0); PG8_BAR; PG8_MMA(0, 0, At, B0); PG8_MMA(0, 1, At, B1); PG8_BAR; PG8_SCHED;
	v_mfma_f32_16x16x32_bf16 v[60:63], v[128:131], v[172:175], v[60:63]
	v_mfma_f32_16x16x32_bf16 v[56:59], v[136:139], v[172:175], v[56:59]
	v_mfma_f32_16x16x32_bf16 v[52:55], v[128:131], v[186:189], v[52:55]
	v_mfma_f32_16x16x32_bf16 v[48:51], v[136:139], v[186:189], v[48:51]
	v_mfma_f32_16x16x32_bf16 v[36:39], v[128:131], v[194:197], v[36:39]
	v_mfma_f32_16x16x32_bf16 v[32:35], v[136:139], v[194:197], v[32:35]
	v_mfma_f32_16x16x32_bf16 v[20:23], v[128:131], v[202:205], v[20:23]
	v_mfma_f32_16x16x32_bf16 v[16:19], v[136:139], v[202:205], v[16:19]
	v_mfma_f32_16x16x32_bf16 v[60:63], v[132:135], v[182:185], v[60:63]
	v_mfma_f32_16x16x32_bf16 v[56:59], v[140:143], v[182:185], v[56:59]
	v_mfma_f32_16x16x32_bf16 v[52:55], v[132:135], v[190:193], v[52:55]
	v_mfma_f32_16x16x32_bf16 v[48:51], v[140:143], v[190:193], v[48:51]
	v_mfma_f32_16x16x32_bf16 v[36:39], v[132:135], v[198:201], v[36:39]
	v_mfma_f32_16x16x32_bf16 v[32:35], v[140:143], v[198:201], v[32:35]
	v_mfma_f32_16x16x32_bf16 v[20:23], v[132:135], v[208:211], v[20:23]
	v_mfma_f32_16x16x32_bf16 v[16:19], v[140:143], v[208:211], v[16:19]
	v_mfma_f32_16x16x32_bf16 v[44:47], v[144:147], v[172:175], v[44:47]
	v_mfma_f32_16x16x32_bf16 v[40:43], v[164:167], v[172:175], v[40:43]
	v_mfma_f32_16x16x32_bf16 v[28:31], v[144:147], v[186:189], v[28:31]
	v_mfma_f32_16x16x32_bf16 v[24:27], v[164:167], v[186:189], v[24:27]
	v_mfma_f32_16x16x32_bf16 v[12:15], v[144:147], v[194:197], v[12:15]
	v_mfma_f32_16x16x32_bf16 v[8:11], v[164:167], v[194:197], v[8:11]
	v_mfma_f32_16x16x32_bf16 v[4:7], v[144:147], v[202:205], v[4:7]
	v_mfma_f32_16x16x32_bf16 v[0:3], v[164:167], v[202:205], v[0:3]
	v_mfma_f32_16x16x32_bf16 v[44:47], v[160:163], v[182:185], v[44:47]
	v_mfma_f32_16x16x32_bf16 v[40:43], v[168:171], v[182:185], v[40:43]
	v_mfma_f32_16x16x32_bf16 v[28:31], v[160:163], v[190:193], v[28:31]
	v_mfma_f32_16x16x32_bf16 v[24:27], v[168:171], v[190:193], v[24:27]
	v_mfma_f32_16x16x32_bf16 v[12:15], v[160:163], v[198:201], v[12:15]
	v_mfma_f32_16x16x32_bf16 v[8:11], v[168:171], v[198:201], v[8:11]
	v_mfma_f32_16x16x32_bf16 v[4:7], v[160:163], v[208:211], v[4:7]
	v_mfma_f32_16x16x32_bf16 v[0:3], v[168:171], v[208:211], v[0:3]
	s_barrier
	s_setprio 1
	v_add_u32_e32 v140, s96, v177
	v_add_u32_e32 v168, s90, v177
	ds_read_b128 v[128:131], v140
	ds_read_b128 v[132:135], v140 offset:1024
	ds_read_b128 v[136:139], v140 offset:2048
	ds_read_b128 v[140:143], v140 offset:3072
	ds_read_b128 v[144:147], v168
	ds_read_b128 v[160:163], v168 offset:1024
	ds_read_b128 v[164:167], v168 offset:2048
	ds_read_b128 v[168:171], v168 offset:3072
	s_add_u32 s18, s20, 0x164000
	s_addc_u32 s19, s21, 0
	s_mov_b32 m0, s29
	v_lshl_add_u64 v[220:221], s[18:19], 0, v[148:149]
	ds_read_b128 v[172:175], v181 offset:32768
	ds_read_b128 v[182:185], v181 offset:33792
	ds_read_b128 v[186:189], v181 offset:34816
	ds_read_b128 v[190:193], v181 offset:35840
	ds_read_b128 v[194:197], v181 offset:36864
	ds_read_b128 v[198:201], v181 offset:37888
	ds_read_b128 v[202:205], v181 offset:38912
	ds_read_b128 v[208:211], v181 offset:39936
	global_load_lds_dwordx4 v[220:221], off
	v_lshl_add_u64 v[220:221], s[18:19], 0, v[152:153]
	s_mov_b32 m0, s97
	s_nop 0
	global_load_lds_dwordx4 v[220:221], off
	s_waitcnt vmcnt(8)
	s_waitcnt lgkmcnt(0)
	s_setprio 0
	s_barrier
	v_mfma_f32_16x16x32_bf16 v[124:127], v[128:131], v[172:175], v[124:127]
	v_mfma_f32_16x16x32_bf16 v[120:123], v[136:139], v[172:175], v[120:123]
	v_mfma_f32_16x16x32_bf16 v[116:119], v[128:131], v[186:189], v[116:119]
	v_mfma_f32_16x16x32_bf16 v[112:115], v[136:139], v[186:189], v[112:115]
	v_mfma_f32_16x16x32_bf16 v[100:103], v[128:131], v[194:197], v[100:103]
	v_mfma_f32_16x16x32_bf16 v[96:99], v[136:139], v[194:197], v[96:99]
	v_mfma_f32_16x16x32_bf16 v[84:87], v[128:131], v[202:205], v[84:87]
	v_mfma_f32_16x16x32_bf16 v[80:83], v[136:139], v[202:205], v[80:83]
	v_mfma_f32_16x16x32_bf16 v[124:127], v[132:135], v[182:185], v[124:127]
	v_mfma_f32_16x16x32_bf16 v[120:123], v[140:143], v[182:185], v[120:123]
	v_mfma_f32_16x16x32_bf16 v[116:119], v[132:135], v[190:193], v[116:119]
	v_mfma_f32_16x16x32_bf16 v[112:115], v[140:143], v[190:193], v[112:115]
	v_mfma_f32_16x16x32_bf16 v[100:103], v[132:135], v[198:201], v[100:103]
	v_mfma_f32_16x16x32_bf16 v[96:99], v[140:143], v[198:201], v[96:99]
	v_mfma_f32_16x16x32_bf16 v[84:87], v[132:135], v[208:211], v[84:87]
	v_mfma_f32_16x16x32_bf16 v[80:83], v[140:143], v[208:211], v[80:83]
	v_mfma_f32_16x16x32_bf16 v[108:111], v[144:147], v[172:175], v[108:111]
	v_mfma_f32_16x16x32_bf16 v[104:107], v[164:167], v[172:175], v[104:107]
	v_mfma_f32_16x16x32_bf16 v[92:95], v[144:147], v[186:189], v[92:95]
	v_mfma_f32_16x16x32_bf16 v[88:91], v[164:167], v[186:189], v[88:91]
	v_mfma_f32_16x16x32_bf16 v[76:79], v[144:147], v[194:197], v[76:79]
	v_mfma_f32_16x16x32_bf16 v[72:75], v[164:167], v[194:197], v[72:75]
	v_mfma_f32_16x16x32_bf16 v[68:71], v[144:147], v[202:205], v[68:71]
	v_mfma_f32_16x16x32_bf16 v[64:67], v[164:167], v[202:205], v[64:67]
	v_mfma_f32_16x16x32_bf16 v[108:111], v[160:163], v[182:185], v[108:111]
	v_mfma_f32_16x16x32_bf16 v[104:107], v[168:171], v[182:185], v[104:107]
	v_mfma_f32_16x16x32_bf16 v[92:95], v[160:163], v[190:193], v[92:95]
	v_mfma_f32_16x16x32_bf16 v[88:91], v[168:171], v[190:193], v[88:91]
	v_mfma_f32_16x16x32_bf16 v[76:79], v[160:163], v[198:201], v[76:79]
	v_mfma_f32_16x16x32_bf16 v[72:75], v[168:171], v[198:201], v[72:75]
	v_mfma_f32_16x16x32_bf16 v[68:71], v[160:163], v[208:211], v[68:71]
	v_mfma_f32_16x16x32_bf16 v[64:67], v[168:171], v[208:211], v[64:67]
	s_barrier
; #define PG8_STAGE(bufoff, gbase, voff) do { _Pragma("unroll") for (int _i = 0; _i < 2; ++_i) \
;         __builtin_amdgcn_global_load_lds((const unsigned*)((const char*)(gbase) + (voff)[_i]), (LAS unsigned*)(lds + (bufoff) + ldsw + _i * 8192), 16, 0, 0); } while (0)
; #define PG8_LDA(dst, b, h) do { _Pragma("unroll") for (int m = 0; m < 4; ++m) _Pragma("unroll") for (int k = 0; k < 2; ++k) dst[m][k] = *(const LAS bf16x8*)(lds + PG8_SA(b, h) + aoff + m * 2048 + k * 1024); } while (0)
; #define PG8_MMA(ai, bj, At, Bt) do { __builtin_amdgcn_s_setprio(1); _Pragma("unroll") for (int m = 0; m < 4; ++m) _Pragma("unroll") for (int n = 0; n < 2; ++n) _Pragma("unroll") for (int k = 0; k < 2; ++k) \
;         acc[ai][bj][m][n] = __builtin_amdgcn_mfma_f32_16x16x32_bf16(Bt[n][k], At[m][k], acc[ai][bj][m][n], 0, 0, 0); __builtin_amdgcn_s_setprio(0); } while (0)
; #define PG8_WAIT_V(n) asm volatile("s_waitcnt vmcnt(" #n ")" ::: "memory")
; #define PG8_WAIT_L(n) asm volatile("s_waitcnt lgkmcnt(" #n ")" ::: "memory")
; #define PG8_BAR __builtin_amdgcn_s_barrier()
; #define PG8_SCHED __builtin_amdgcn_sched_barrier(0)
; template <class Epi, class Sched>
; DI void gemm_phase(LAS unsigned char* lds, const int K, const Sched& S, const Epi& E, const int wid) {
;     ...
;             PG8_LDA(At, 1, 1); PG8_STAGE(PG8_SB(1, 0), b3, voffB); PG8_STAGE(PG8_SB(1, 1), b3 + hstep, voffB); PG8_STAGE(PG8_SA(1, 0), a3, voffA);
;             PG8_WAIT_V(8); PG8_WAIT_L(0); PG8_BAR; PG8_MMA(1, 0, At, B0); PG8_MMA(1, 1, At, B1); PG8_BAR; PG8_SCHED;
;         }
;         if (wr == 0) PG8_BAR;
	s_setprio 1
	s_mov_b32 m0, s94
	v_lshl_add_u64 v[212:213], v[212:213], 0, s[10:11]
	s_add_u32 s6, s6, 0x164080
	ds_read_b128 v[172:175], v181 offset:49152
	ds_read_b128 v[182:185], v181 offset:50176
	ds_read_b128 v[186:189], v181 offset:51200
	ds_read_b128 v[190:193], v181 offset:52224
	ds_read_b128 v[194:197], v181 offset:53248
	ds_read_b128 v[198:201], v181 offset:54272
	ds_read_b128 v[202:205], v181 offset:55296
	ds_read_b128 v[208:211], v181 offset:56320
	global_load_lds_dwordx4 v[212:213], off
	v_lshl_add_u64 v[212:213], v[214:215], 0, s[10:11]
	s_mov_b32 m0, s84
	s_addc_u32 s7, s7, 0
	global_load_lds_dwordx4 v[212:213], off
	v_lshl_add_u64 v[212:213], s[6:7], 0, v[150:151]
	s_mov_b32 m0, s86
	s_nop 0
	global_load_lds_dwordx4 v[212:213], off
	v_lshl_add_u64 v[212:213], s[6:7], 0, v[154:155]
	s_mov_b32 m0, s28
	s_nop 0
	global_load_lds_dwordx4 v[212:213], off
	v_lshl_add_u64 v[212:213], v[216:217], 0, s[10:11]
	s_mov_b32 m0, s91
	s_nop 0
	global_load_lds_dwordx4 v[212:213], off
	v_lshl_add_u64 v[212:213], v[218:219], 0, s[10:11]
	s_mov_b32 m0, s88
	s_nop 0
	global_load_lds_dwordx4 v[212:213], off
	s_waitcnt vmcnt(8)
	s_waitcnt lgkmcnt(0)
	s_setprio 0
	s_barrier
	v_mfma_f32_16x16x32_bf16 v[60:63], v[128:131], v[172:175], v[60:63]
	v_mfma_f32_16x16x32_bf16 v[56:59], v[136:139], v[172:175], v[56:59]
	v_mfma_f32_16x16x32_bf16 v[52:55], v[128:131], v[186:189], v[52:55]
	v_mfma_f32_16x16x32_bf16 v[48:51], v[136:139], v[186:189], v[48:51]
	v_mfma_f32_16x16x32_bf16 v[36:39], v[128:131], v[194:197], v[36:39]
	v_mfma_f32_16x16x32_bf16 v[32:35], v[136:139], v[194:197], v[32:35]
	v_mfma_f32_16x16x32_bf16 v[20:23], v[128:131], v[202:205], v[20:23]
	v_mfma_f32_16x16x32_bf16 v[16:19], v[136:139], v[202:205], v[16:19]
	v_mfma_f32_16x16x32_bf16 v[60:63], v[132:135], v[182:185], v[60:63]
	v_mfma_f32_16x16x32_bf16 v[56:59], v[140:143], v[182:185], v[56:59]
	v_mfma_f32_16x16x32_bf16 v[52:55], v[132:135], v[190:193], v[52:55]
	v_mfma_f32_16x16x32_bf16 v[48:51], v[140:143], v[190:193], v[48:51]
	v_mfma_f32_16x16x32_bf16 v[36:39], v[132:135], v[198:201], v[36:39]
	v_mfma_f32_16x16x32_bf16 v[32:35], v[140:143], v[198:201], v[32:35]
	v_mfma_f32_16x16x32_bf16 v[20:23], v[132:135], v[208:211], v[20:23]
	v_mfma_f32_16x16x32_bf16 v[16:19], v[140:143], v[208:211], v[16:19]
	v_mfma_f32_16x16x32_bf16 v[44:47], v[144:147], v[172:175], v[44:47]
	v_mfma_f32_16x16x32_bf16 v[40:43], v[164:167], v[172:175], v[40:43]
	v_mfma_f32_16x16x32_bf16 v[28:31], v[144:147], v[186:189], v[28:31]
	v_mfma_f32_16x16x32_bf16 v[24:27], v[164:167], v[186:189], v[24:27]
	v_mfma_f32_16x16x32_bf16 v[12:15], v[144:147], v[194:197], v[12:15]
	v_mfma_f32_16x16x32_bf16 v[8:11], v[164:167], v[194:197], v[8:11]
	v_mfma_f32_16x16x32_bf16 v[4:7], v[144:147], v[202:205], v[4:7]
	v_mfma_f32_16x16x32_bf16 v[0:3], v[164:167], v[202:205], v[0:3]
	v_mfma_f32_16x16x32_bf16 v[44:47], v[160:163], v[182:185], v[44:47]
	v_mfma_f32_16x16x32_bf16 v[40:43], v[168:171], v[182:185], v[40:43]
	v_mfma_f32_16x16x32_bf16 v[28:31], v[160:163], v[190:193], v[28:31]
	v_mfma_f32_16x16x32_bf16 v[24:27], v[168:171], v[190:193], v[24:27]
	v_mfma_f32_16x16x32_bf16 v[12:15], v[160:163], v[198:201], v[12:15]
	v_mfma_f32_16x16x32_bf16 v[8:11], v[168:171], v[198:201], v[8:11]
	v_mfma_f32_16x16x32_bf16 v[4:7], v[160:163], v[208:211], v[4:7]
	v_mfma_f32_16x16x32_bf16 v[0:3], v[168:171], v[208:211], v[0:3]
	s_barrier
	s_setprio 1
	s_add_u32 s36, s36, 0x100
	s_addc_u32 s37, s37, 0
	s_cmp_ge_u32 s38, s34
	s_mov_b64 s[18:19], s[4:5]
	s_mov_b32 s6, s38
	s_cbranch_scc0 .LBB0_1068
	v_readlane_b32 s4, v249, 25
	v_readlane_b32 s5, v249, 26
	s_and_b64 vcc, exec, s[4:5]
	s_cbranch_vccz .LBB0_1071
	s_barrier
